# GEMM K-loops: one static s_setprio 1 for waves 4-7 before each loop (priority 0 again after it), per-phase s_setprio flips inside the loops deleted
# speedup vs baseline: 1.0198x; 1.0198x over previous
; #define PG8_STAGE(bufoff, gbase, voff) do { _Pragma("unroll") for (int _i = 0; _i < 2; ++_i) \
;         __builtin_amdgcn_global_load_lds((const unsigned*)((const char*)(gbase) + (voff)[_i]), (LAS unsigned*)(lds + (bufoff) + ldsw + _i * 8192), 16, 0, 0); } while (0)
; #define PG8_LDA(dst, b, h) do { _Pragma("unroll") for (int m = 0; m < 4; ++m) _Pragma("unroll") for (int k = 0; k < 2; ++k) dst[m][k] = *(const LAS bf16x8*)(lds + PG8_SA(b, h) + aoff + m * 2048 + k * 1024); } while (0)
; #define PG8_LDB(dst, b, h) do { _Pragma("unroll") for (int n = 0; n < 2; ++n) _Pragma("unroll") for (int k = 0; k < 2; ++k) dst[n][k] = *(const LAS bf16x8*)(lds + PG8_SB(b, h) + boff + n * 2048 + k * 1024); } while (0)
; #define PG8_MMA(ai, bj, At, Bt) do { __builtin_amdgcn_s_setprio(1); _Pragma("unroll") for (int m = 0; m < 4; ++m) _Pragma("unroll") for (int n = 0; n < 2; ++n) _Pragma("unroll") for (int k = 0; k < 2; ++k) \
;         acc[ai][bj][m][n] = __builtin_amdgcn_mfma_f32_16x16x32_bf16(Bt[n][k], At[m][k], acc[ai][bj][m][n], 0, 0, 0); __builtin_amdgcn_s_setprio(0); } while (0)
; #define PG8_WAIT_L(n) asm volatile("s_waitcnt lgkmcnt(" #n ")" ::: "memory")
; template <class Epi>
; __device__ __forceinline__ void gemm_phase(LAS unsigned char* lds, const Gemm g, const StaticOrder& S, const Epi& E) {
;     ...
;     for (;;) {
;         const bool has_next = S.next(ui + 1, nxt);
;         const char* nA = has_next ? (const char*)g.A + (size_t)nxt.pm * tstep : cA; const char* nB = has_next ? (const char*)g.Bt + (size_t)nxt.pn * tstep : cB;
;         for (int t = 0; t < nt; t += 2) {
;             const bool last = (t == nt - 2);
;             const char* a1 = cA + (size_t)(t + 1) * kstep;
;             const char* a2 = last ? nA : cA + (size_t)(t + 2) * kstep; const char* b2 = last ? nB : cB + (size_t)(t + 2) * kstep;
;             const char* a3 = a2 + kstep; const char* b3 = b2 + kstep;
;             PG8_LDB(B0, 0, 0); PG8_SCHED; PG8_LDA(At, 0, 0); PG8_STAGE(PG8_SA(1, 1), a1 + hstep, voffA);
;             PG8_WAIT_L(8); PG8_BAR; PG8_WAIT_L(0); PG8_MMA(0, 0, At, B0); PG8_BAR; PG8_SCHED;
;             PG8_LDB(B1, 0, 1); PG8_STAGE(PG8_SB(0, 0), b2, voffB);
;             PG8_BAR; PG8_WAIT_L(0); PG8_MMA(0, 1, At, B1); PG8_BAR;
;             PG8_LDA(At, 0, 1); PG8_STAGE(PG8_SA(0, 0), a2, voffA);
;             PG8_BAR; PG8_WAIT_L(0); PG8_MMA(1, 0, At, B0); PG8_BAR; PG8_SCHED;
.LBB0_163:
	s_add_u32 s70, s60, 0x100
	s_addc_u32 s71, s61, 0
	s_add_u32 s48, s46, 0xb0080
	s_addc_u32 s49, s47, 0
	v_lshl_add_u64 v[136:137], s[48:49], 0, v[132:133]
	v_lshl_add_u64 v[138:139], s[48:49], 0, v[134:135]
	s_mov_b32 s93, -2
	s_mov_b64 s[60:61], 0
	s_cmpk_gt_u32 s30, 0xff
	s_cbranch_scc0 .Lprio_164
	s_setprio 1
.Lprio_164:
.LBB0_164:
	s_add_u32 s48, s46, s60
	s_addc_u32 s49, s47, s61
	s_add_u32 s48, s48, 0x100
	s_addc_u32 s49, s49, 0
	s_add_u32 s56, s70, s60
	s_addc_u32 s57, s71, s61
	s_add_i32 s58, 0, 0x10000
	v_add_u32_e32 v140, s58, v143
	ds_read_b128 v[148:151], v140
	ds_read_b128 v[152:155], v140 offset:1024
	ds_read_b128 v[156:159], v140 offset:2048
	ds_read_b128 v[172:175], v140 offset:3072
	s_cmpk_eq_i32 s60, 0x1500
	s_cselect_b32 s51, s37, s49
	s_cselect_b32 s50, s36, s48
	s_cselect_b32 s49, s45, s57
	s_cselect_b32 s48, s44, s56
	v_lshl_add_u64 v[140:141], v[136:137], 0, s[60:61]
	s_add_i32 m0, s53, 0xc000
	ds_read_b128 v[178:181], v147
	ds_read_b128 v[182:185], v147 offset:1024
	ds_read_b128 v[186:189], v147 offset:2048
	ds_read_b128 v[190:193], v147 offset:3072
	ds_read_b128 v[194:197], v147 offset:4096
	ds_read_b128 v[198:201], v147 offset:5120
	ds_read_b128 v[202:205], v147 offset:6144
	ds_read_b128 v[206:209], v147 offset:7168
	global_load_lds_dwordx4 v[140:141], off
	v_lshl_add_u64 v[140:141], v[138:139], 0, s[60:61]
	s_add_i32 m0, s53, 0xe000
	s_nop 0
	global_load_lds_dwordx4 v[140:141], off
	s_waitcnt lgkmcnt(8)
	s_barrier
	s_waitcnt lgkmcnt(0)
	s_waitcnt lgkmcnt(0)
	v_mfma_f32_16x16x32_bf16 v[126:129], v[148:151], v[178:181], v[126:129]
	v_mfma_f32_16x16x32_bf16 v[122:125], v[156:159], v[178:181], v[122:125]
	v_mfma_f32_16x16x32_bf16 v[110:113], v[148:151], v[186:189], v[110:113]
	v_mfma_f32_16x16x32_bf16 v[106:109], v[156:159], v[186:189], v[106:109]
	v_mfma_f32_16x16x32_bf16 v[94:97], v[148:151], v[194:197], v[94:97]
	v_mfma_f32_16x16x32_bf16 v[90:93], v[156:159], v[194:197], v[90:93]
	v_mfma_f32_16x16x32_bf16 v[78:81], v[148:151], v[202:205], v[78:81]
	v_mfma_f32_16x16x32_bf16 v[74:77], v[156:159], v[202:205], v[74:77]
	v_mfma_f32_16x16x32_bf16 v[126:129], v[152:155], v[182:185], v[126:129]
	v_mfma_f32_16x16x32_bf16 v[122:125], v[172:175], v[182:185], v[122:125]
	v_mfma_f32_16x16x32_bf16 v[110:113], v[152:155], v[190:193], v[110:113]
	v_mfma_f32_16x16x32_bf16 v[106:109], v[172:175], v[190:193], v[106:109]
	v_mfma_f32_16x16x32_bf16 v[94:97], v[152:155], v[198:201], v[94:97]
	v_mfma_f32_16x16x32_bf16 v[90:93], v[172:175], v[198:201], v[90:93]
	v_mfma_f32_16x16x32_bf16 v[78:81], v[152:155], v[206:209], v[78:81]
	v_mfma_f32_16x16x32_bf16 v[74:77], v[172:175], v[206:209], v[74:77]
	s_barrier
	s_add_i32 s56, 0, 0x14000
	v_add_u32_e32 v140, s56, v143
	s_add_i32 s57, s58, s52
	ds_read_b128 v[210:213], v140
	ds_read_b128 v[214:217], v140 offset:1024
	ds_read_b128 v[218:221], v140 offset:2048
	ds_read_b128 v[246:249], v140 offset:3072
	v_lshl_add_u64 v[140:141], s[48:49], 0, v[0:1]
	s_mov_b32 m0, s57
	v_lshl_add_u64 v[160:161], s[48:49], 0, v[130:131]
	global_load_lds_dwordx4 v[140:141], off
	s_add_i32 m0, s57, 0x2000
	s_nop 0
	global_load_lds_dwordx4 v[160:161], off
	s_barrier
	s_waitcnt lgkmcnt(0)
	s_waitcnt lgkmcnt(0)
	v_mfma_f32_16x16x32_bf16 v[118:121], v[210:213], v[178:181], v[118:121]
	v_mfma_f32_16x16x32_bf16 v[114:117], v[218:221], v[178:181], v[114:117]
	v_mfma_f32_16x16x32_bf16 v[102:105], v[210:213], v[186:189], v[102:105]
	v_mfma_f32_16x16x32_bf16 v[98:101], v[218:221], v[186:189], v[98:101]
	v_mfma_f32_16x16x32_bf16 v[86:89], v[210:213], v[194:197], v[86:89]
	v_mfma_f32_16x16x32_bf16 v[82:85], v[218:221], v[194:197], v[82:85]
	v_mfma_f32_16x16x32_bf16 v[70:73], v[210:213], v[202:205], v[70:73]
	v_mfma_f32_16x16x32_bf16 v[66:69], v[218:221], v[202:205], v[66:69]
	v_mfma_f32_16x16x32_bf16 v[118:121], v[214:217], v[182:185], v[118:121]
	v_mfma_f32_16x16x32_bf16 v[114:117], v[246:249], v[182:185], v[114:117]
	v_mfma_f32_16x16x32_bf16 v[102:105], v[214:217], v[190:193], v[102:105]
	v_mfma_f32_16x16x32_bf16 v[98:101], v[246:249], v[190:193], v[98:101]
	v_mfma_f32_16x16x32_bf16 v[86:89], v[214:217], v[198:201], v[86:89]
	v_mfma_f32_16x16x32_bf16 v[82:85], v[246:249], v[198:201], v[82:85]
	v_mfma_f32_16x16x32_bf16 v[70:73], v[214:217], v[206:209], v[70:73]
	v_mfma_f32_16x16x32_bf16 v[66:69], v[246:249], v[206:209], v[66:69]
	s_mov_b32 m0, s53
	v_lshl_add_u64 v[222:223], s[50:51], 0, v[0:1]
	s_barrier
	ds_read_b128 v[178:181], v147 offset:16384
	ds_read_b128 v[182:185], v147 offset:17408
	ds_read_b128 v[186:189], v147 offset:18432
	ds_read_b128 v[190:193], v147 offset:19456
	ds_read_b128 v[194:197], v147 offset:20480
	ds_read_b128 v[198:201], v147 offset:21504
	ds_read_b128 v[202:205], v147 offset:22528
	ds_read_b128 v[206:209], v147 offset:23552
	global_load_lds_dwordx4 v[222:223], off
	v_lshl_add_u64 v[236:237], s[50:51], 0, v[130:131]
	s_mov_b32 m0, s54
	s_nop 0
	global_load_lds_dwordx4 v[236:237], off
	s_barrier
	s_waitcnt lgkmcnt(0)
	s_waitcnt lgkmcnt(0)
	v_mfma_f32_16x16x32_bf16 v[62:65], v[148:151], v[178:181], v[62:65]
	v_mfma_f32_16x16x32_bf16 v[58:61], v[156:159], v[178:181], v[58:61]
	v_mfma_f32_16x16x32_bf16 v[46:49], v[148:151], v[186:189], v[46:49]
	v_mfma_f32_16x16x32_bf16 v[42:45], v[156:159], v[186:189], v[42:45]
	v_mfma_f32_16x16x32_bf16 v[30:33], v[148:151], v[194:197], v[30:33]
	v_mfma_f32_16x16x32_bf16 v[26:29], v[156:159], v[194:197], v[26:29]
	v_mfma_f32_16x16x32_bf16 v[14:17], v[148:151], v[202:205], v[14:17]
	v_mfma_f32_16x16x32_bf16 v[10:13], v[156:159], v[202:205], v[10:13]
	v_mfma_f32_16x16x32_bf16 v[62:65], v[152:155], v[182:185], v[62:65]
	v_mfma_f32_16x16x32_bf16 v[58:61], v[172:175], v[182:185], v[58:61]
	v_mfma_f32_16x16x32_bf16 v[46:49], v[152:155], v[190:193], v[46:49]
	v_mfma_f32_16x16x32_bf16 v[42:45], v[172:175], v[190:193], v[42:45]
	v_mfma_f32_16x16x32_bf16 v[30:33], v[152:155], v[198:201], v[30:33]
	v_mfma_f32_16x16x32_bf16 v[26:29], v[172:175], v[198:201], v[26:29]
	v_mfma_f32_16x16x32_bf16 v[14:17], v[152:155], v[206:209], v[14:17]
	v_mfma_f32_16x16x32_bf16 v[10:13], v[172:175], v[206:209], v[10:13]
	s_barrier
; #define PG8_STAGE(bufoff, gbase, voff) do { _Pragma("unroll") for (int _i = 0; _i < 2; ++_i) \
;         __builtin_amdgcn_global_load_lds((const unsigned*)((const char*)(gbase) + (voff)[_i]), (LAS unsigned*)(lds + (bufoff) + ldsw + _i * 8192), 16, 0, 0); } while (0)
; #define PG8_LDA(dst, b, h) do { _Pragma("unroll") for (int m = 0; m < 4; ++m) _Pragma("unroll") for (int k = 0; k < 2; ++k) dst[m][k] = *(const LAS bf16x8*)(lds + PG8_SA(b, h) + aoff + m * 2048 + k * 1024); } while (0)
; #define PG8_LDB(dst, b, h) do { _Pragma("unroll") for (int n = 0; n < 2; ++n) _Pragma("unroll") for (int k = 0; k < 2; ++k) dst[n][k] = *(const LAS bf16x8*)(lds + PG8_SB(b, h) + boff + n * 2048 + k * 1024); } while (0)
; #define PG8_MMA(ai, bj, At, Bt) do { __builtin_amdgcn_s_setprio(1); _Pragma("unroll") for (int m = 0; m < 4; ++m) _Pragma("unroll") for (int n = 0; n < 2; ++n) _Pragma("unroll") for (int k = 0; k < 2; ++k) \
;         acc[ai][bj][m][n] = __builtin_amdgcn_mfma_f32_16x16x32_bf16(Bt[n][k], At[m][k], acc[ai][bj][m][n], 0, 0, 0); __builtin_amdgcn_s_setprio(0); } while (0)
; #define PG8_WAIT_V(n) asm volatile("s_waitcnt vmcnt(" #n ")" ::: "memory")
; #define PG8_WAIT_L(n) asm volatile("s_waitcnt lgkmcnt(" #n ")" ::: "memory")
; #define PG8_BAR __builtin_amdgcn_s_barrier()
; #define PG8_SCHED __builtin_amdgcn_sched_barrier(0)
; template <class Epi>
; __device__ __forceinline__ void gemm_phase(LAS unsigned char* lds, const Gemm g, const StaticOrder& S, const Epi& E) {
;     ...
;             PG8_STAGE(PG8_SB(0, 1), b2 + hstep, voffB);
;             PG8_WAIT_V(6); PG8_BAR; PG8_MMA(1, 1, At, B1); PG8_BAR;
;             PG8_LDB(B0, 1, 0); PG8_SCHED; PG8_LDA(At, 1, 0); PG8_STAGE(PG8_SA(0, 1), a2 + hstep, voffA);
;             PG8_WAIT_L(8); PG8_BAR; PG8_WAIT_L(0); PG8_MMA(0, 0, At, B0); PG8_BAR; PG8_SCHED;
;             PG8_LDB(B1, 1, 1); PG8_STAGE(PG8_SB(1, 0), b3, voffB);
;             PG8_BAR; PG8_WAIT_L(0); PG8_MMA(0, 1, At, B1); PG8_BAR;
;             PG8_LDA(At, 1, 1); PG8_STAGE(PG8_SA(1, 0), a3, voffA);
;             PG8_BAR; PG8_WAIT_L(0); PG8_MMA(1, 0, At, B0); PG8_BAR; PG8_SCHED;
	s_add_u32 s58, s48, 0xb0000
	s_addc_u32 s59, s49, 0
	s_add_i32 s56, s56, s52
	v_lshl_add_u64 v[148:149], s[58:59], 0, v[0:1]
	s_mov_b32 m0, s56
	s_nop 0
	global_load_lds_dwordx4 v[148:149], off
	v_lshl_add_u64 v[148:149], s[58:59], 0, v[130:131]
	s_add_i32 m0, s56, 0x2000
	s_nop 0
	global_load_lds_dwordx4 v[148:149], off
	s_waitcnt vmcnt(6)
	s_barrier
	v_mfma_f32_16x16x32_bf16 v[54:57], v[210:213], v[178:181], v[54:57]
	v_mfma_f32_16x16x32_bf16 v[50:53], v[218:221], v[178:181], v[50:53]
	v_mfma_f32_16x16x32_bf16 v[38:41], v[210:213], v[186:189], v[38:41]
	v_mfma_f32_16x16x32_bf16 v[34:37], v[218:221], v[186:189], v[34:37]
	v_mfma_f32_16x16x32_bf16 v[22:25], v[210:213], v[194:197], v[22:25]
	v_mfma_f32_16x16x32_bf16 v[18:21], v[218:221], v[194:197], v[18:21]
	v_mfma_f32_16x16x32_bf16 v[6:9], v[210:213], v[202:205], v[6:9]
	v_mfma_f32_16x16x32_bf16 v[2:5], v[218:221], v[202:205], v[2:5]
	v_mfma_f32_16x16x32_bf16 v[54:57], v[214:217], v[182:185], v[54:57]
	v_mfma_f32_16x16x32_bf16 v[50:53], v[246:249], v[182:185], v[50:53]
	v_mfma_f32_16x16x32_bf16 v[38:41], v[214:217], v[190:193], v[38:41]
	v_mfma_f32_16x16x32_bf16 v[34:37], v[246:249], v[190:193], v[34:37]
	v_mfma_f32_16x16x32_bf16 v[22:25], v[214:217], v[198:201], v[22:25]
	v_mfma_f32_16x16x32_bf16 v[18:21], v[246:249], v[198:201], v[18:21]
	v_mfma_f32_16x16x32_bf16 v[6:9], v[214:217], v[206:209], v[6:9]
	v_mfma_f32_16x16x32_bf16 v[2:5], v[246:249], v[206:209], v[2:5]
	s_add_i32 s56, 0, 0x18000
	v_add_u32_e32 v172, s56, v143
	s_barrier
	ds_read_b128 v[148:151], v172
	ds_read_b128 v[152:155], v172 offset:1024
	ds_read_b128 v[156:159], v172 offset:2048
	ds_read_b128 v[172:175], v172 offset:3072
	s_add_u32 s50, s50, 0xb0000
	s_addc_u32 s51, s51, 0
	s_mov_b32 m0, s55
	v_lshl_add_u64 v[210:211], s[50:51], 0, v[0:1]
	ds_read_b128 v[178:181], v147 offset:32768
	ds_read_b128 v[182:185], v147 offset:33792
	ds_read_b128 v[186:189], v147 offset:34816
	ds_read_b128 v[190:193], v147 offset:35840
	ds_read_b128 v[194:197], v147 offset:36864
	ds_read_b128 v[198:201], v147 offset:37888
	ds_read_b128 v[202:205], v147 offset:38912
	ds_read_b128 v[206:209], v147 offset:39936
	global_load_lds_dwordx4 v[210:211], off
	v_lshl_add_u64 v[210:211], s[50:51], 0, v[130:131]
	s_mov_b32 m0, s63
	s_nop 0
	global_load_lds_dwordx4 v[210:211], off
	s_waitcnt lgkmcnt(8)
	s_barrier
	s_waitcnt lgkmcnt(0)
	s_waitcnt lgkmcnt(0)
	v_mfma_f32_16x16x32_bf16 v[126:129], v[148:151], v[178:181], v[126:129]
	v_mfma_f32_16x16x32_bf16 v[122:125], v[156:159], v[178:181], v[122:125]
	v_mfma_f32_16x16x32_bf16 v[110:113], v[148:151], v[186:189], v[110:113]
	v_mfma_f32_16x16x32_bf16 v[106:109], v[156:159], v[186:189], v[106:109]
	v_mfma_f32_16x16x32_bf16 v[94:97], v[148:151], v[194:197], v[94:97]
	v_mfma_f32_16x16x32_bf16 v[90:93], v[156:159], v[194:197], v[90:93]
	v_mfma_f32_16x16x32_bf16 v[78:81], v[148:151], v[202:205], v[78:81]
	v_mfma_f32_16x16x32_bf16 v[74:77], v[156:159], v[202:205], v[74:77]
	v_mfma_f32_16x16x32_bf16 v[126:129], v[152:155], v[182:185], v[126:129]
	v_mfma_f32_16x16x32_bf16 v[122:125], v[172:175], v[182:185], v[122:125]
	v_mfma_f32_16x16x32_bf16 v[110:113], v[152:155], v[190:193], v[110:113]
	v_mfma_f32_16x16x32_bf16 v[106:109], v[172:175], v[190:193], v[106:109]
	v_mfma_f32_16x16x32_bf16 v[94:97], v[152:155], v[198:201], v[94:97]
	v_mfma_f32_16x16x32_bf16 v[90:93], v[172:175], v[198:201], v[90:93]
	v_mfma_f32_16x16x32_bf16 v[78:81], v[152:155], v[206:209], v[78:81]
	v_mfma_f32_16x16x32_bf16 v[74:77], v[172:175], v[206:209], v[74:77]
	s_barrier
	s_add_i32 s50, 0, 0x1c000
	s_add_i32 s51, s56, s52
	v_add_u32_e32 v177, s50, v143
	v_lshl_add_u64 v[140:141], v[140:141], 0, s[28:29]
	s_mov_b32 m0, s51
	ds_read_b128 v[210:213], v177
	ds_read_b128 v[214:217], v177 offset:1024
	ds_read_b128 v[218:221], v177 offset:2048
	ds_read_b128 v[246:249], v177 offset:3072
	global_load_lds_dwordx4 v[140:141], off
	v_lshl_add_u64 v[140:141], v[160:161], 0, s[28:29]
	s_add_i32 m0, s51, 0x2000
	s_nop 0
	global_load_lds_dwordx4 v[140:141], off
	s_barrier
	s_waitcnt lgkmcnt(0)
	s_waitcnt lgkmcnt(0)
	v_mfma_f32_16x16x32_bf16 v[118:121], v[210:213], v[178:181], v[118:121]
	v_mfma_f32_16x16x32_bf16 v[114:117], v[218:221], v[178:181], v[114:117]
	v_mfma_f32_16x16x32_bf16 v[102:105], v[210:213], v[186:189], v[102:105]
	v_mfma_f32_16x16x32_bf16 v[98:101], v[218:221], v[186:189], v[98:101]
	v_mfma_f32_16x16x32_bf16 v[86:89], v[210:213], v[194:197], v[86:89]
	v_mfma_f32_16x16x32_bf16 v[82:85], v[218:221], v[194:197], v[82:85]
	v_mfma_f32_16x16x32_bf16 v[70:73], v[210:213], v[202:205], v[70:73]
	v_mfma_f32_16x16x32_bf16 v[66:69], v[218:221], v[202:205], v[66:69]
	v_mfma_f32_16x16x32_bf16 v[118:121], v[214:217], v[182:185], v[118:121]
	v_mfma_f32_16x16x32_bf16 v[114:117], v[246:249], v[182:185], v[114:117]
	v_mfma_f32_16x16x32_bf16 v[102:105], v[214:217], v[190:193], v[102:105]
	v_mfma_f32_16x16x32_bf16 v[98:101], v[246:249], v[190:193], v[98:101]
	v_mfma_f32_16x16x32_bf16 v[86:89], v[214:217], v[198:201], v[86:89]
	v_mfma_f32_16x16x32_bf16 v[82:85], v[246:249], v[198:201], v[82:85]
	v_mfma_f32_16x16x32_bf16 v[70:73], v[214:217], v[206:209], v[70:73]
	v_mfma_f32_16x16x32_bf16 v[66:69], v[246:249], v[206:209], v[66:69]
	s_mov_b32 m0, s64
	v_lshl_add_u64 v[140:141], v[222:223], 0, s[28:29]
	s_barrier
	ds_read_b128 v[178:181], v147 offset:49152
	ds_read_b128 v[182:185], v147 offset:50176
	ds_read_b128 v[186:189], v147 offset:51200
	ds_read_b128 v[190:193], v147 offset:52224
	ds_read_b128 v[194:197], v147 offset:53248
	ds_read_b128 v[198:201], v147 offset:54272
	ds_read_b128 v[202:205], v147 offset:55296
	ds_read_b128 v[206:209], v147 offset:56320
	global_load_lds_dwordx4 v[140:141], off
	v_lshl_add_u64 v[140:141], v[236:237], 0, s[28:29]
	s_mov_b32 m0, s65
	s_nop 0
	global_load_lds_dwordx4 v[140:141], off
	s_barrier
; __device__ __forceinline__ u64 ss_fix(float ss) { return (u64)(ss * 1048576.f + 0.5f); }
; __device__ __forceinline__ unsigned pk2(float lo, float hi) { unsigned r; asm volatile("v_cvt_pk_bf16_f32 %0, %1, %2" : "=v"(r) : "v"(lo), "v"(hi)); return r; }
; __device__ __forceinline__ float shfl_xor_(float v, int o, int lane) { return shfl_idx(v, lane ^ o); }
; #define PG8_STAGE(bufoff, gbase, voff) do { _Pragma("unroll") for (int _i = 0; _i < 2; ++_i) \
;         __builtin_amdgcn_global_load_lds((const unsigned*)((const char*)(gbase) + (voff)[_i]), (LAS unsigned*)(lds + (bufoff) + ldsw + _i * 8192), 16, 0, 0); } while (0)
; #define PG8_WAIT_V(n) asm volatile("s_waitcnt vmcnt(" #n ")" ::: "memory")
; #define PG8_BAR __builtin_amdgcn_s_barrier()
; template <class Epi>
; __device__ __forceinline__ void gemm_phase(LAS unsigned char* lds, const Gemm g, const StaticOrder& S, const Epi& E) {
;     ...
;             PG8_BAR; PG8_WAIT_L(0); PG8_MMA(1, 0, At, B0); PG8_BAR; PG8_SCHED;
;             PG8_STAGE(PG8_SB(1, 1), b3 + hstep, voffB);
;             PG8_WAIT_V(6); PG8_BAR; PG8_MMA(1, 1, At, B1); PG8_BAR;
;         }
;         if constexpr (Epi::AFTER_DRAIN) { if (has_next) E(acc, cur, wr, wc, fr, fq); } else E(acc, cur, wr, wc, fr, fq);
;     __device__ __forceinline__ void operator()(const f32x4 (&acc)[2][2][4][2], const Unit& u, int wr, int wc, int fr, int fq) const {
;         const int row0 = u.pm * BM + wr * 64 + fr, col0 = u.pn * BM + wc * 32 + 4 * fq, lane = fr | (fq << 4);
; #pragma unroll
;         for (int ai = 0; ai < 2; ++ai)
; #pragma unroll
;             for (int m = 0; m < 4; ++m) { const int row = row0 + ai * HALF + m * 16; bf16_t* xbp = xb + (size_t)row * ldc + col0;
;                 float ss = 0.f;
; #pragma unroll
;                 for (int bj = 0; bj < 2; ++bj)
; #pragma unroll
;                     for (int n = 0; n < 2; ++n) { u32x2* pp = (u32x2*)(xbp + bj * HALF + n * 16); float o[4]; unpack4(*pp, o);
;                         u32x2 w; w.x = pk2(o[0] + acc[ai][bj][m][n][0], o[1] + acc[ai][bj][m][n][1]); w.y = pk2(o[2] + acc[ai][bj][m][n][2], o[3] + acc[ai][bj][m][n][3]); *pp = w;
;                         unpack4(w, o); ss += o[0] * o[0] + o[1] * o[1] + o[2] * o[2] + o[3] * o[3]; }
;                 ss += shfl_xor_(ss, 16, lane); ss += shfl_xor_(ss, 32, lane);
;                 if (fq == 0) atomicAdd(rss + row, ss_fix(ss)); }
	s_waitcnt lgkmcnt(0)
	s_waitcnt lgkmcnt(0)
	v_mfma_f32_16x16x32_bf16 v[62:65], v[148:151], v[178:181], v[62:65]
	v_mfma_f32_16x16x32_bf16 v[58:61], v[156:159], v[178:181], v[58:61]
	v_mfma_f32_16x16x32_bf16 v[46:49], v[148:151], v[186:189], v[46:49]
	v_mfma_f32_16x16x32_bf16 v[42:45], v[156:159], v[186:189], v[42:45]
	v_mfma_f32_16x16x32_bf16 v[30:33], v[148:151], v[194:197], v[30:33]
	v_mfma_f32_16x16x32_bf16 v[26:29], v[156:159], v[194:197], v[26:29]
	v_mfma_f32_16x16x32_bf16 v[14:17], v[148:151], v[202:205], v[14:17]
	v_mfma_f32_16x16x32_bf16 v[10:13], v[156:159], v[202:205], v[10:13]
	v_mfma_f32_16x16x32_bf16 v[62:65], v[152:155], v[182:185], v[62:65]
	v_mfma_f32_16x16x32_bf16 v[58:61], v[172:175], v[182:185], v[58:61]
	v_mfma_f32_16x16x32_bf16 v[46:49], v[152:155], v[190:193], v[46:49]
	v_mfma_f32_16x16x32_bf16 v[42:45], v[172:175], v[190:193], v[42:45]
	v_mfma_f32_16x16x32_bf16 v[30:33], v[152:155], v[198:201], v[30:33]
	v_mfma_f32_16x16x32_bf16 v[26:29], v[172:175], v[198:201], v[26:29]
	v_mfma_f32_16x16x32_bf16 v[14:17], v[152:155], v[206:209], v[14:17]
	v_mfma_f32_16x16x32_bf16 v[10:13], v[172:175], v[206:209], v[10:13]
	s_barrier
	s_add_u32 s48, s48, 0xb0080
	s_addc_u32 s49, s49, 0
	s_add_i32 s50, s50, s52
	v_lshl_add_u64 v[140:141], s[48:49], 0, v[0:1]
	s_mov_b32 m0, s50
	s_nop 0
	global_load_lds_dwordx4 v[140:141], off
	v_lshl_add_u64 v[140:141], s[48:49], 0, v[130:131]
	s_add_i32 m0, s50, 0x2000
	s_nop 0
	global_load_lds_dwordx4 v[140:141], off
	s_waitcnt vmcnt(6)
	s_barrier
	v_mfma_f32_16x16x32_bf16 v[54:57], v[210:213], v[178:181], v[54:57]
	v_mfma_f32_16x16x32_bf16 v[50:53], v[218:221], v[178:181], v[50:53]
	v_mfma_f32_16x16x32_bf16 v[38:41], v[210:213], v[186:189], v[38:41]
	v_mfma_f32_16x16x32_bf16 v[34:37], v[218:221], v[186:189], v[34:37]
	v_mfma_f32_16x16x32_bf16 v[22:25], v[210:213], v[194:197], v[22:25]
	v_mfma_f32_16x16x32_bf16 v[18:21], v[218:221], v[194:197], v[18:21]
	v_mfma_f32_16x16x32_bf16 v[6:9], v[210:213], v[202:205], v[6:9]
	v_mfma_f32_16x16x32_bf16 v[2:5], v[218:221], v[202:205], v[2:5]
	v_mfma_f32_16x16x32_bf16 v[54:57], v[214:217], v[182:185], v[54:57]
	v_mfma_f32_16x16x32_bf16 v[50:53], v[246:249], v[182:185], v[50:53]
	v_mfma_f32_16x16x32_bf16 v[38:41], v[214:217], v[190:193], v[38:41]
	v_mfma_f32_16x16x32_bf16 v[34:37], v[246:249], v[190:193], v[34:37]
	v_mfma_f32_16x16x32_bf16 v[22:25], v[214:217], v[198:201], v[22:25]
	v_mfma_f32_16x16x32_bf16 v[18:21], v[246:249], v[198:201], v[18:21]
	v_mfma_f32_16x16x32_bf16 v[6:9], v[214:217], v[206:209], v[6:9]
	v_mfma_f32_16x16x32_bf16 v[2:5], v[246:249], v[206:209], v[2:5]
	s_add_i32 s93, s93, 2
	s_add_u32 s60, s60, 0x100
	s_addc_u32 s61, s61, 0
	s_cmp_gt_u32 s93, 41
	s_barrier
	s_cbranch_scc0 .LBB0_164
	s_setprio 0
	s_add_u32 s48, s70, 0xffffff00
	s_addc_u32 s49, s71, -1
	s_and_b64 vcc, exec, s[0:1]
	s_movk_i32 s93, 0x1000
	s_cbranch_vccz .LBB0_183
	v_lshl_add_u32 v140, s68, 8, v142
	v_ashrrev_i32_e32 v141, 31, v140
	v_readlane_b32 s0, v252, 51
	v_lshl_or_b32 v138, s67, 8, v144
	v_lshlrev_b64 v[136:137], 11, v[140:141]
	v_readlane_b32 s1, v252, 52
	v_ashrrev_i32_e32 v139, 31, v138
	s_nop 0
	v_lshl_add_u64 v[136:137], s[0:1], 0, v[136:137]
	v_lshl_add_u64 v[136:137], v[138:139], 1, v[136:137]
	global_load_dwordx2 v[148:149], v[136:137], off
	s_waitcnt vmcnt(0)
	v_lshlrev_b32_e32 v150, 16, v148
	v_and_b32_e32 v148, 0xffff0000, v148
	v_lshlrev_b32_e32 v151, 16, v149
	v_and_b32_e32 v149, 0xffff0000, v149
	v_add_f32_e32 v126, v126, v150
	v_add_f32_e32 v127, v127, v148
	v_add_f32_e32 v128, v128, v151
	v_add_f32_e32 v129, v129, v149
	v_cvt_pk_bf16_f32 v126, v126, v127
	v_cvt_pk_bf16_f32 v127, v128, v129
	global_load_dwordx2 v[128:129], v[136:137], off offset:32
	s_waitcnt vmcnt(0)
	v_lshlrev_b32_e32 v148, 16, v128
	v_and_b32_e32 v128, 0xffff0000, v128
	v_lshlrev_b32_e32 v149, 16, v129
	v_and_b32_e32 v129, 0xffff0000, v129
	v_add_f32_e32 v122, v122, v148
	v_add_f32_e32 v123, v123, v128
	v_add_f32_e32 v124, v124, v149
	v_add_f32_e32 v125, v125, v129
	global_store_dwordx2 v[136:137], v[126:127], off
	v_cvt_pk_bf16_f32 v122, v122, v123
	v_cvt_pk_bf16_f32 v123, v124, v125
	global_load_dwordx2 v[124:125], v[136:137], off offset:256
	s_waitcnt vmcnt(0)
	v_lshlrev_b32_e32 v128, 16, v124
	v_and_b32_e32 v124, 0xffff0000, v124
	v_lshlrev_b32_e32 v129, 16, v125
	v_and_b32_e32 v125, 0xffff0000, v125
	v_add_f32_e32 v118, v118, v128
	v_add_f32_e32 v119, v119, v124
	v_add_f32_e32 v120, v120, v129
	v_add_f32_e32 v121, v121, v125
	global_store_dwordx2 v[136:137], v[122:123], off offset:32
	v_cvt_pk_bf16_f32 v118, v118, v119
	v_cvt_pk_bf16_f32 v119, v120, v121
	global_load_dwordx2 v[120:121], v[136:137], off offset:288
	v_and_b32_e32 v125, 0xffff0000, v126
	v_lshlrev_b32_e32 v124, 16, v126
	v_mul_f32_e32 v125, v125, v125
	v_fmac_f32_e32 v125, v124, v124
	v_lshlrev_b32_e32 v124, 16, v122
	v_and_b32_e32 v122, 0xffff0000, v122
	v_lshlrev_b32_e32 v126, 16, v127
	v_mul_f32_e32 v122, v122, v122
	v_fmac_f32_e32 v125, v126, v126
	v_lshlrev_b32_e32 v126, 16, v123
	v_fmac_f32_e32 v122, v124, v124
	v_and_b32_e32 v123, 0xffff0000, v123
	v_fmac_f32_e32 v122, v126, v126
	v_fmac_f32_e32 v122, v123, v123
	global_store_dwordx2 v[136:137], v[118:119], off offset:256
	v_lshlrev_b32_e32 v123, 16, v118
	v_and_b32_e32 v118, 0xffff0000, v118
	v_mul_f32_e32 v118, v118, v118
	v_and_b32_e32 v127, 0xffff0000, v127
	v_lshlrev_b32_e32 v124, 16, v119
	v_fmac_f32_e32 v118, v123, v123
	v_fmac_f32_e32 v125, v127, v127
	v_and_b32_e32 v119, 0xffff0000, v119
	v_fmac_f32_e32 v118, v124, v124
	v_add_f32_e32 v122, v125, v122
	v_fmac_f32_e32 v118, v119, v119
	v_add_f32_e32 v118, v122, v118
	s_waitcnt vmcnt(0)
	v_lshlrev_b32_e32 v119, 16, v120
	v_and_b32_e32 v120, 0xffff0000, v120
	v_lshlrev_b32_e32 v122, 16, v121
	v_and_b32_e32 v121, 0xffff0000, v121
	v_add_f32_e32 v114, v114, v119
	v_add_f32_e32 v115, v115, v120
	v_add_f32_e32 v117, v117, v121
	v_add_f32_e32 v116, v116, v122
	v_cvt_pk_bf16_f32 v114, v114, v115
	v_cvt_pk_bf16_f32 v115, v116, v117
	global_store_dwordx2 v[136:137], v[114:115], off offset:288
	v_and_b32_e32 v117, 0xffff0000, v114
	v_lshlrev_b32_e32 v116, 16, v114
	v_mul_f32_e32 v117, v117, v117
	v_lshlrev_b32_e32 v119, 16, v115
	v_fmac_f32_e32 v117, v116, v116
	v_and_b32_e32 v120, 0xffff0000, v115
	v_fmac_f32_e32 v117, v119, v119
	v_fmac_f32_e32 v117, v120, v120
	v_add_f32_e32 v116, v118, v117
	ds_bpermute_b32 v117, v145, v116
	v_lshl_add_u64 v[114:115], v[140:141], 3, s[72:73]
	s_waitcnt lgkmcnt(0)
	v_add_f32_e32 v116, v116, v117
	ds_bpermute_b32 v117, v146, v116
	s_and_saveexec_b64 s[0:1], s[40:41]
	v_readlane_b32 s84, v254, 44
	v_readlane_b32 s85, v254, 45
	s_cbranch_execz .LBB0_168
	s_waitcnt lgkmcnt(0)
	v_add_f32_e32 v116, v116, v117
	s_mov_b32 s46, 0x49800000
	v_fma_f32 v116, v116, s46, 0.5
	v_trunc_f32_e32 v116, v116
	v_mul_f32_e32 v117, 0x2f800000, v116
	v_floor_f32_e32 v117, v117
	v_fmac_f32_e32 v116, 0xcf800000, v117
	v_cvt_u32_f32_e32 v116, v116
	v_cvt_u32_f32_e32 v117, v117
	global_atomic_add_x2 v[114:115], v[116:117], off

; #define PG8_STAGE(bufoff, gbase, voff) do { _Pragma("unroll") for (int _i = 0; _i < 2; ++_i) \
;         __builtin_amdgcn_global_load_lds((const unsigned*)((const char*)(gbase) + (voff)[_i]), (LAS unsigned*)(lds + (bufoff) + ldsw + _i * 8192), 16, 0, 0); } while (0)
; #define PG8_LDA(dst, b, h) do { _Pragma("unroll") for (int m = 0; m < 4; ++m) _Pragma("unroll") for (int k = 0; k < 2; ++k) dst[m][k] = *(const LAS bf16x8*)(lds + PG8_SA(b, h) + aoff + m * 2048 + k * 1024); } while (0)
; #define PG8_LDB(dst, b, h) do { _Pragma("unroll") for (int n = 0; n < 2; ++n) _Pragma("unroll") for (int k = 0; k < 2; ++k) dst[n][k] = *(const LAS bf16x8*)(lds + PG8_SB(b, h) + boff + n * 2048 + k * 1024); } while (0)
; #define PG8_MMA(ai, bj, At, Bt) do { __builtin_amdgcn_s_setprio(1); _Pragma("unroll") for (int m = 0; m < 4; ++m) _Pragma("unroll") for (int n = 0; n < 2; ++n) _Pragma("unroll") for (int k = 0; k < 2; ++k) \
;         acc[ai][bj][m][n] = __builtin_amdgcn_mfma_f32_16x16x32_bf16(Bt[n][k], At[m][k], acc[ai][bj][m][n], 0, 0, 0); __builtin_amdgcn_s_setprio(0); } while (0)
; #define PG8_WAIT_V(n) asm volatile("s_waitcnt vmcnt(" #n ")" ::: "memory")
; #define PG8_WAIT_L(n) asm volatile("s_waitcnt lgkmcnt(" #n ")" ::: "memory")
; template <class Epi>
; __device__ __forceinline__ void gemm_phase(LAS unsigned char* lds, const Gemm g, const StaticOrder& S, const Epi& E) {
;     ...
;         for (int t = 0; t < nt; t += 2) {
;             const bool last = (t == nt - 2);
;             const char* a1 = cA + (size_t)(t + 1) * kstep;
;             const char* a2 = last ? nA : cA + (size_t)(t + 2) * kstep; const char* b2 = last ? nB : cB + (size_t)(t + 2) * kstep;
;             const char* a3 = a2 + kstep; const char* b3 = b2 + kstep;
;             PG8_LDB(B0, 0, 0); PG8_SCHED; PG8_LDA(At, 0, 0); PG8_STAGE(PG8_SA(1, 1), a1 + hstep, voffA);
;             PG8_WAIT_L(8); PG8_BAR; PG8_WAIT_L(0); PG8_MMA(0, 0, At, B0); PG8_BAR; PG8_SCHED;
;             PG8_LDB(B1, 0, 1); PG8_STAGE(PG8_SB(0, 0), b2, voffB);
;             PG8_BAR; PG8_WAIT_L(0); PG8_MMA(0, 1, At, B1); PG8_BAR;
;             PG8_LDA(At, 0, 1); PG8_STAGE(PG8_SA(0, 0), a2, voffA);
;             PG8_BAR; PG8_WAIT_L(0); PG8_MMA(1, 0, At, B0); PG8_BAR; PG8_SCHED;
;             PG8_STAGE(PG8_SB(0, 1), b2 + hstep, voffB);
;             PG8_WAIT_V(6); PG8_BAR; PG8_MMA(1, 1, At, B1); PG8_BAR;
.Lst5_done:
	s_cmpk_gt_u32 s72, 0xff
	s_cbranch_scc0 .Lprio_211
	s_setprio 1
.Lprio_211:
.LBB0_211:
	s_add_u32 s36, s0, 0xfffc0080
	s_addc_u32 s37, s1, -1
	s_add_i32 s58, 0, 0x10000
	v_add_u32_e32 v0, s58, v171
	ds_read_b128 v[42:45], v0
	ds_read_b128 v[46:49], v0 offset:1024
	ds_read_b128 v[50:53], v0 offset:2048
	ds_read_b128 v[54:57], v0 offset:3072
	s_cmp_eq_u32 s24, 12
	s_cselect_b32 s53, s65, s37
	s_cselect_b32 s52, s96, s36
	s_cselect_b32 s37, s63, vcc_hi
	s_cselect_b32 s36, s97, vcc_lo
	v_lshl_add_u64 v[202:203], s[0:1], 0, v[186:187]
	s_add_i32 m0, s30, 0xc000
	ds_read_b128 v[58:61], v242
	ds_read_b128 v[62:65], v242 offset:1024
	ds_read_b128 v[70:73], v242 offset:2048
	ds_read_b128 v[74:77], v242 offset:3072
	ds_read_b128 v[172:175], v242 offset:4096
	ds_read_b128 v[190:193], v242 offset:5120
	ds_read_b128 v[194:197], v242 offset:6144
	ds_read_b128 v[198:201], v242 offset:7168
	global_load_lds_dwordx4 v[202:203], off
	v_lshl_add_u64 v[202:203], s[0:1], 0, v[188:189]
	s_add_i32 m0, s30, 0xe000
	s_nop 0
	global_load_lds_dwordx4 v[202:203], off
	s_waitcnt lgkmcnt(8)
	s_barrier
	s_waitcnt lgkmcnt(0)
	s_waitcnt lgkmcnt(0)
	v_mfma_f32_16x16x32_bf16 v[158:161], v[42:45], v[58:61], v[158:161]
	v_mfma_f32_16x16x32_bf16 v[154:157], v[50:53], v[58:61], v[154:157]
	v_mfma_f32_16x16x32_bf16 v[142:145], v[42:45], v[70:73], v[142:145]
	v_mfma_f32_16x16x32_bf16 v[138:141], v[50:53], v[70:73], v[138:141]
	v_mfma_f32_16x16x32_bf16 v[126:129], v[42:45], v[172:175], v[126:129]
	v_mfma_f32_16x16x32_bf16 v[122:125], v[50:53], v[172:175], v[122:125]
	v_mfma_f32_16x16x32_bf16 v[110:113], v[42:45], v[194:197], v[110:113]
	v_mfma_f32_16x16x32_bf16 v[106:109], v[50:53], v[194:197], v[106:109]
	v_mfma_f32_16x16x32_bf16 v[158:161], v[46:49], v[62:65], v[158:161]
	v_mfma_f32_16x16x32_bf16 v[154:157], v[54:57], v[62:65], v[154:157]
	v_mfma_f32_16x16x32_bf16 v[142:145], v[46:49], v[74:77], v[142:145]
	v_mfma_f32_16x16x32_bf16 v[138:141], v[54:57], v[74:77], v[138:141]
	v_mfma_f32_16x16x32_bf16 v[126:129], v[46:49], v[190:193], v[126:129]
	v_mfma_f32_16x16x32_bf16 v[122:125], v[54:57], v[190:193], v[122:125]
	v_mfma_f32_16x16x32_bf16 v[110:113], v[46:49], v[198:201], v[110:113]
	v_mfma_f32_16x16x32_bf16 v[106:109], v[54:57], v[198:201], v[106:109]
	s_barrier
	s_add_i32 s56, 0, 0x14000
	s_add_i32 s57, s58, s26
	v_add_u32_e32 v0, s56, v171
	v_lshl_add_u64 v[222:223], s[36:37], 0, v[180:181]
	s_mov_b32 m0, s57
	ds_read_b128 v[202:205], v0
	ds_read_b128 v[206:209], v0 offset:1024
	ds_read_b128 v[210:213], v0 offset:2048
	ds_read_b128 v[214:217], v0 offset:3072
	global_load_lds_dwordx4 v[222:223], off
	v_lshl_add_u64 v[246:247], s[36:37], 0, v[176:177]
	s_add_i32 m0, s57, 0x2000
	s_nop 0
	global_load_lds_dwordx4 v[246:247], off
	s_barrier
	s_waitcnt lgkmcnt(0)
	s_waitcnt lgkmcnt(0)
	v_mfma_f32_16x16x32_bf16 v[150:153], v[202:205], v[58:61], v[150:153]
	v_mfma_f32_16x16x32_bf16 v[58:61], v[210:213], v[58:61], v[146:149]
	v_mfma_f32_16x16x32_bf16 v[150:153], v[206:209], v[62:65], v[150:153]
	v_mfma_f32_16x16x32_bf16 v[58:61], v[214:217], v[62:65], v[58:61]
	v_mfma_f32_16x16x32_bf16 v[62:65], v[202:205], v[70:73], v[130:133]
	v_mfma_f32_16x16x32_bf16 v[70:73], v[210:213], v[70:73], v[134:137]
	v_mfma_f32_16x16x32_bf16 v[62:65], v[206:209], v[74:77], v[62:65]
	v_mfma_f32_16x16x32_bf16 v[70:73], v[214:217], v[74:77], v[70:73]
	v_mfma_f32_16x16x32_bf16 v[74:77], v[202:205], v[172:175], v[114:117]
	v_mfma_f32_16x16x32_bf16 v[114:117], v[210:213], v[172:175], v[118:121]
	v_mfma_f32_16x16x32_bf16 v[98:101], v[202:205], v[194:197], v[98:101]
	v_mfma_f32_16x16x32_bf16 v[102:105], v[210:213], v[194:197], v[102:105]
	v_mfma_f32_16x16x32_bf16 v[118:121], v[214:217], v[190:193], v[114:117]
	v_mfma_f32_16x16x32_bf16 v[98:101], v[206:209], v[198:201], v[98:101]
	v_mfma_f32_16x16x32_bf16 v[102:105], v[214:217], v[198:201], v[102:105]
	v_mfma_f32_16x16x32_bf16 v[74:77], v[206:209], v[190:193], v[74:77]
	s_mov_b32 m0, s30
	v_lshl_add_u64 v[248:249], s[52:53], 0, v[182:183]
	s_barrier
	ds_read_b128 v[114:117], v242 offset:16384
	ds_read_b128 v[130:133], v242 offset:17408
	ds_read_b128 v[134:137], v242 offset:18432
	ds_read_b128 v[146:149], v242 offset:19456
	ds_read_b128 v[172:175], v242 offset:20480
	ds_read_b128 v[190:193], v242 offset:21504
	ds_read_b128 v[194:197], v242 offset:22528
	ds_read_b128 v[198:201], v242 offset:23552
	global_load_lds_dwordx4 v[248:249], off
	v_lshl_add_u64 v[236:237], s[52:53], 0, v[178:179]
	s_mov_b32 m0, s54
	s_nop 0
	global_load_lds_dwordx4 v[236:237], off
	s_barrier
	s_waitcnt lgkmcnt(0)
	s_waitcnt lgkmcnt(0)
	v_mfma_f32_16x16x32_bf16 v[94:97], v[42:45], v[114:117], v[94:97]
	v_mfma_f32_16x16x32_bf16 v[90:93], v[50:53], v[114:117], v[90:93]
	v_mfma_f32_16x16x32_bf16 v[78:81], v[42:45], v[134:137], v[78:81]
	v_mfma_f32_16x16x32_bf16 v[66:69], v[50:53], v[134:137], v[66:69]
	v_mfma_f32_16x16x32_bf16 v[30:33], v[42:45], v[172:175], v[30:33]
	v_mfma_f32_16x16x32_bf16 v[26:29], v[50:53], v[172:175], v[26:29]
	v_mfma_f32_16x16x32_bf16 v[14:17], v[42:45], v[194:197], v[14:17]
	v_mfma_f32_16x16x32_bf16 v[10:13], v[50:53], v[194:197], v[10:13]
	v_mfma_f32_16x16x32_bf16 v[94:97], v[46:49], v[130:133], v[94:97]
	v_mfma_f32_16x16x32_bf16 v[90:93], v[54:57], v[130:133], v[90:93]
	v_mfma_f32_16x16x32_bf16 v[78:81], v[46:49], v[146:149], v[78:81]
	v_mfma_f32_16x16x32_bf16 v[66:69], v[54:57], v[146:149], v[66:69]
	v_mfma_f32_16x16x32_bf16 v[30:33], v[46:49], v[190:193], v[30:33]
	v_mfma_f32_16x16x32_bf16 v[26:29], v[54:57], v[190:193], v[26:29]
	v_mfma_f32_16x16x32_bf16 v[14:17], v[46:49], v[198:201], v[14:17]
	v_mfma_f32_16x16x32_bf16 v[10:13], v[54:57], v[198:201], v[10:13]
	s_barrier
	s_add_u32 s58, s36, 0x40000
	s_addc_u32 s59, s37, 0
	s_add_i32 s56, s56, s26
	v_lshl_add_u64 v[42:43], s[58:59], 0, v[180:181]
	s_mov_b32 m0, s56
	s_nop 0
	global_load_lds_dwordx4 v[42:43], off
	v_lshl_add_u64 v[42:43], s[58:59], 0, v[176:177]
	s_add_i32 m0, s56, 0x2000
	s_nop 0
	global_load_lds_dwordx4 v[42:43], off
	s_cmp_lg_u32 s24, -2
	s_cbranch_scc1 .Lrx_s5_std
	s_cmp_lt_u32 s95, 2
	s_cbranch_scc1 .Lrx_s5_std
	s_waitcnt vmcnt(22)
	s_branch .Lrx_s5_done

; #define PG8_STAGE(bufoff, gbase, voff) do { _Pragma("unroll") for (int _i = 0; _i < 2; ++_i) \
;         __builtin_amdgcn_global_load_lds((const unsigned*)((const char*)(gbase) + (voff)[_i]), (LAS unsigned*)(lds + (bufoff) + ldsw + _i * 8192), 16, 0, 0); } while (0)
; #define PG8_LDA(dst, b, h) do { _Pragma("unroll") for (int m = 0; m < 4; ++m) _Pragma("unroll") for (int k = 0; k < 2; ++k) dst[m][k] = *(const LAS bf16x8*)(lds + PG8_SA(b, h) + aoff + m * 2048 + k * 1024); } while (0)
; #define PG8_LDB(dst, b, h) do { _Pragma("unroll") for (int n = 0; n < 2; ++n) _Pragma("unroll") for (int k = 0; k < 2; ++k) dst[n][k] = *(const LAS bf16x8*)(lds + PG8_SB(b, h) + boff + n * 2048 + k * 1024); } while (0)
; #define PG8_MMA(ai, bj, At, Bt) do { __builtin_amdgcn_s_setprio(1); _Pragma("unroll") for (int m = 0; m < 4; ++m) _Pragma("unroll") for (int n = 0; n < 2; ++n) _Pragma("unroll") for (int k = 0; k < 2; ++k) \
;         acc[ai][bj][m][n] = __builtin_amdgcn_mfma_f32_16x16x32_bf16(Bt[n][k], At[m][k], acc[ai][bj][m][n], 0, 0, 0); __builtin_amdgcn_s_setprio(0); } while (0)
; #define PG8_WAIT_V(n) asm volatile("s_waitcnt vmcnt(" #n ")" ::: "memory")
; #define PG8_WAIT_L(n) asm volatile("s_waitcnt lgkmcnt(" #n ")" ::: "memory")
; #define PG8_BAR __builtin_amdgcn_s_barrier()
; #define PG8_SCHED __builtin_amdgcn_sched_barrier(0)
; template <class Epi>
; __device__ __forceinline__ void gemm_phase(LAS unsigned char* lds, const Gemm g, const StaticOrder& S, const Epi& E) {
;     ...
;             PG8_WAIT_V(6); PG8_BAR; PG8_MMA(1, 1, At, B1); PG8_BAR;
;             PG8_LDB(B0, 1, 0); PG8_SCHED; PG8_LDA(At, 1, 0); PG8_STAGE(PG8_SA(0, 1), a2 + hstep, voffA);
;             PG8_WAIT_L(8); PG8_BAR; PG8_WAIT_L(0); PG8_MMA(0, 0, At, B0); PG8_BAR; PG8_SCHED;
;             PG8_LDB(B1, 1, 1); PG8_STAGE(PG8_SB(1, 0), b3, voffB);
;             PG8_BAR; PG8_WAIT_L(0); PG8_MMA(0, 1, At, B1); PG8_BAR;
;             PG8_LDA(At, 1, 1); PG8_STAGE(PG8_SA(1, 0), a3, voffA);
;             PG8_BAR; PG8_WAIT_L(0); PG8_MMA(1, 0, At, B0); PG8_BAR; PG8_SCHED;
.Lrx_s5_done:
	s_barrier
	v_mfma_f32_16x16x32_bf16 v[34:37], v[202:205], v[134:137], v[34:37]
	v_mfma_f32_16x16x32_bf16 v[38:41], v[210:213], v[134:137], v[38:41]
	v_mfma_f32_16x16x32_bf16 v[18:21], v[202:205], v[172:175], v[18:21]
	v_mfma_f32_16x16x32_bf16 v[22:25], v[210:213], v[172:175], v[22:25]
	v_mfma_f32_16x16x32_bf16 v[2:5], v[202:205], v[194:197], v[2:5]
	v_mfma_f32_16x16x32_bf16 v[6:9], v[210:213], v[194:197], v[6:9]
	v_mfma_f32_16x16x32_bf16 v[42:45], v[202:205], v[114:117], v[86:89]
	v_mfma_f32_16x16x32_bf16 v[46:49], v[210:213], v[114:117], v[82:85]
	v_mfma_f32_16x16x32_bf16 v[34:37], v[206:209], v[146:149], v[34:37]
	v_mfma_f32_16x16x32_bf16 v[38:41], v[214:217], v[146:149], v[38:41]
	v_mfma_f32_16x16x32_bf16 v[18:21], v[206:209], v[190:193], v[18:21]
	v_mfma_f32_16x16x32_bf16 v[22:25], v[214:217], v[190:193], v[22:25]
	v_mfma_f32_16x16x32_bf16 v[2:5], v[206:209], v[198:201], v[2:5]
	v_mfma_f32_16x16x32_bf16 v[6:9], v[214:217], v[198:201], v[6:9]
	v_mfma_f32_16x16x32_bf16 v[42:45], v[206:209], v[130:133], v[42:45]
	v_mfma_f32_16x16x32_bf16 v[46:49], v[214:217], v[130:133], v[46:49]
	s_add_i32 s56, 0, 0x18000
	v_add_u32_e32 v0, s56, v171
	s_barrier
	ds_read_b128 v[50:53], v0
	ds_read_b128 v[54:57], v0 offset:1024
	ds_read_b128 v[82:85], v0 offset:2048
	ds_read_b128 v[86:89], v0 offset:3072
	s_add_u32 s52, s52, 0x40000
	s_addc_u32 s53, s53, 0
	s_mov_b32 m0, s55
	v_lshl_add_u64 v[146:147], s[52:53], 0, v[182:183]
	ds_read_b128 v[114:117], v242 offset:32768
	ds_read_b128 v[130:133], v242 offset:33792
	ds_read_b128 v[134:137], v242 offset:34816
	ds_read_b128 v[172:175], v242 offset:35840
	ds_read_b128 v[190:193], v242 offset:36864
	ds_read_b128 v[194:197], v242 offset:37888
	ds_read_b128 v[198:201], v242 offset:38912
	ds_read_b128 v[202:205], v242 offset:39936
	global_load_lds_dwordx4 v[146:147], off
	v_lshl_add_u64 v[146:147], s[52:53], 0, v[178:179]
	s_mov_b32 m0, s70
	s_nop 0
	global_load_lds_dwordx4 v[146:147], off
	s_waitcnt lgkmcnt(8)
	s_barrier
	s_waitcnt lgkmcnt(0)
	s_waitcnt lgkmcnt(0)
	v_mfma_f32_16x16x32_bf16 v[146:149], v[50:53], v[114:117], v[158:161]
	v_mfma_f32_16x16x32_bf16 v[158:161], v[54:57], v[130:133], v[146:149]
	v_mfma_f32_16x16x32_bf16 v[146:149], v[82:85], v[114:117], v[154:157]
	v_mfma_f32_16x16x32_bf16 v[142:145], v[50:53], v[134:137], v[142:145]
	v_mfma_f32_16x16x32_bf16 v[138:141], v[82:85], v[134:137], v[138:141]
	v_mfma_f32_16x16x32_bf16 v[126:129], v[50:53], v[190:193], v[126:129]
	v_mfma_f32_16x16x32_bf16 v[122:125], v[82:85], v[190:193], v[122:125]
	v_mfma_f32_16x16x32_bf16 v[110:113], v[50:53], v[198:201], v[110:113]
	v_mfma_f32_16x16x32_bf16 v[106:109], v[82:85], v[198:201], v[106:109]
	v_mfma_f32_16x16x32_bf16 v[154:157], v[86:89], v[130:133], v[146:149]
	v_mfma_f32_16x16x32_bf16 v[142:145], v[54:57], v[172:175], v[142:145]
	v_mfma_f32_16x16x32_bf16 v[138:141], v[86:89], v[172:175], v[138:141]
	v_mfma_f32_16x16x32_bf16 v[126:129], v[54:57], v[194:197], v[126:129]
	v_mfma_f32_16x16x32_bf16 v[122:125], v[86:89], v[194:197], v[122:125]
	v_mfma_f32_16x16x32_bf16 v[110:113], v[54:57], v[202:205], v[110:113]
	v_mfma_f32_16x16x32_bf16 v[106:109], v[86:89], v[202:205], v[106:109]
	s_barrier
	s_add_i32 s52, 0, 0x1c000
	s_add_i32 s53, s56, s26
	v_add_u32_e32 v0, s52, v171
	v_lshl_add_u64 v[146:147], v[222:223], 0, s[28:29]
	s_mov_b32 m0, s53
	ds_read_b128 v[206:209], v0
	ds_read_b128 v[210:213], v0 offset:1024
	ds_read_b128 v[214:217], v0 offset:2048
	ds_read_b128 v[218:221], v0 offset:3072
	global_load_lds_dwordx4 v[146:147], off
	v_lshl_add_u64 v[146:147], v[246:247], 0, s[28:29]
	s_add_i32 m0, s53, 0x2000
	s_nop 0
	global_load_lds_dwordx4 v[146:147], off
	s_barrier
	s_waitcnt lgkmcnt(0)
	s_waitcnt lgkmcnt(0)
	v_mfma_f32_16x16x32_bf16 v[146:149], v[206:209], v[114:117], v[150:153]
	v_mfma_f32_16x16x32_bf16 v[58:61], v[214:217], v[114:117], v[58:61]
	v_mfma_f32_16x16x32_bf16 v[150:153], v[210:213], v[130:133], v[146:149]
	v_mfma_f32_16x16x32_bf16 v[146:149], v[218:221], v[130:133], v[58:61]
	v_mfma_f32_16x16x32_bf16 v[58:61], v[206:209], v[134:137], v[62:65]
	v_mfma_f32_16x16x32_bf16 v[130:133], v[210:213], v[172:175], v[58:61]
	v_mfma_f32_16x16x32_bf16 v[58:61], v[214:217], v[134:137], v[70:73]
	v_mfma_f32_16x16x32_bf16 v[134:137], v[218:221], v[172:175], v[58:61]
	v_mfma_f32_16x16x32_bf16 v[58:61], v[206:209], v[190:193], v[74:77]
	v_mfma_f32_16x16x32_bf16 v[114:117], v[210:213], v[194:197], v[58:61]
	v_mfma_f32_16x16x32_bf16 v[58:61], v[214:217], v[190:193], v[118:121]
	v_mfma_f32_16x16x32_bf16 v[118:121], v[218:221], v[194:197], v[58:61]
	v_mfma_f32_16x16x32_bf16 v[58:61], v[206:209], v[198:201], v[98:101]
	v_mfma_f32_16x16x32_bf16 v[98:101], v[210:213], v[202:205], v[58:61]
	v_mfma_f32_16x16x32_bf16 v[58:61], v[214:217], v[198:201], v[102:105]
	v_mfma_f32_16x16x32_bf16 v[102:105], v[218:221], v[202:205], v[58:61]
	s_mov_b32 m0, s93
	v_lshl_add_u64 v[202:203], v[248:249], 0, s[28:29]
	s_waitcnt vmcnt(10)
	s_barrier
	s_nop 2
	ds_read_b128 v[58:61], v242 offset:49152
	ds_read_b128 v[62:65], v242 offset:50176
	ds_read_b128 v[70:73], v242 offset:51200
	ds_read_b128 v[74:77], v242 offset:52224
	ds_read_b128 v[172:175], v242 offset:53248
	ds_read_b128 v[190:193], v242 offset:54272
	ds_read_b128 v[194:197], v242 offset:55296
	ds_read_b128 v[198:201], v242 offset:56320
	global_load_lds_dwordx4 v[202:203], off
	v_lshl_add_u64 v[202:203], v[236:237], 0, s[28:29]
	s_mov_b32 m0, s94
	s_nop 0
	global_load_lds_dwordx4 v[202:203], off
	s_barrier
; #define PG8_BAR __builtin_amdgcn_s_barrier()
; template <class Epi>
; __device__ __forceinline__ void gemm_phase(LAS unsigned char* lds, const Gemm g, const StaticOrder& S, const Epi& E) {
;     ...
;             PG8_BAR; PG8_WAIT_L(0); PG8_MMA(1, 0, At, B0); PG8_BAR; PG8_SCHED;
;             PG8_STAGE(PG8_SB(1, 1), b3 + hstep, voffB);
;             PG8_WAIT_V(6); PG8_BAR; PG8_MMA(1, 1, At, B1); PG8_BAR;
;         }
;         if constexpr (Epi::AFTER_DRAIN) { if (has_next) E(acc, cur, wr, wc, fr, fq); } else E(acc, cur, wr, wc, fr, fq);
;     __device__ __forceinline__ void operator()(const f32x4 (&acc)[2][2][4][2], const Unit& u, int wr, int wc, int fr, int fq) const {
;         const int row0 = u.pm * BM + wr * 64 + fr, f0 = u.pn * HALF + wc * 32 + 8 * fq;
;         float w0[8], w1[8], w2[8], bb[8];
;         *(f32x4*)w0 = *(const f32x4*)(cw + f0); *(f32x4*)(w0 + 4) = *(const f32x4*)(cw + f0 + 4);
;         *(f32x4*)w1 = *(const f32x4*)(cw + DFF + f0); *(f32x4*)(w1 + 4) = *(const f32x4*)(cw + DFF + f0 + 4);
;         *(f32x4*)w2 = *(const f32x4*)(cw + 2 * DFF + f0); *(f32x4*)(w2 + 4) = *(const f32x4*)(cw + 2 * DFF + f0 + 4);
;         *(f32x4*)bb = *(const f32x4*)(cb + f0); *(f32x4*)(bb + 4) = *(const f32x4*)(cb + f0 + 4);
;         u64 rv[2][4];
; #pragma unroll
;         for (int ai = 0; ai < 2; ++ai)
; #pragma unroll
;             for (int m = 0; m < 4; ++m) rv[ai][m] = rss[row0 + ai * HALF + m * 16];
; #pragma unroll
;         for (int ai = 0; ai < 2; ++ai) {
;             float gp[8];
; #pragma unroll
;             for (int e = 0; e < 8; ++e) gp[e] = 0.f;
; #pragma unroll
;             for (int m = 0; m < 4; ++m) {
;                 const int row = row0 + ai * HALF + m * 16;
;                 const float rs = rstd_fix(rv[ai][m]);
;                 float g[8], up[8], o[8];
;                 { const f32x4 g0 = acc[ai][0][m][0] * rs, g1 = acc[ai][0][m][1] * rs, u0 = acc[ai][1][m][0] * rs, u1 = acc[ai][1][m][1] * rs;
; #pragma unroll
;                   for (int i = 0; i < 4; ++i) { g[i] = g0[i]; g[4 + i] = g1[i]; up[i] = u0[i]; up[4 + i] = u1[i]; } }
; #pragma unroll
;                 for (int e2 = 0; e2 < 4; ++e2) {
;                     const int e = 2 * e2;
;                     const f32x2 gv = {g[e], g[e + 1]};
;                     const f32x2 g1v = {dpp_shr<1>(dpp_ror<1>(gp[e]), g[e]), dpp_shr<1>(dpp_ror<1>(gp[e + 1]), g[e + 1])};
	s_waitcnt lgkmcnt(0)
	s_waitcnt lgkmcnt(0)
	v_mfma_f32_16x16x32_bf16 v[94:97], v[50:53], v[58:61], v[94:97]
	v_mfma_f32_16x16x32_bf16 v[90:93], v[82:85], v[58:61], v[90:93]
	v_mfma_f32_16x16x32_bf16 v[78:81], v[50:53], v[70:73], v[78:81]
	v_mfma_f32_16x16x32_bf16 v[66:69], v[82:85], v[70:73], v[66:69]
	v_mfma_f32_16x16x32_bf16 v[30:33], v[50:53], v[172:175], v[30:33]
	v_mfma_f32_16x16x32_bf16 v[26:29], v[82:85], v[172:175], v[26:29]
	v_mfma_f32_16x16x32_bf16 v[14:17], v[50:53], v[194:197], v[14:17]
	v_mfma_f32_16x16x32_bf16 v[10:13], v[82:85], v[194:197], v[10:13]
	v_mfma_f32_16x16x32_bf16 v[94:97], v[54:57], v[62:65], v[94:97]
	v_mfma_f32_16x16x32_bf16 v[90:93], v[86:89], v[62:65], v[90:93]
	v_mfma_f32_16x16x32_bf16 v[78:81], v[54:57], v[74:77], v[78:81]
	v_mfma_f32_16x16x32_bf16 v[66:69], v[86:89], v[74:77], v[66:69]
	v_mfma_f32_16x16x32_bf16 v[30:33], v[54:57], v[190:193], v[30:33]
	v_mfma_f32_16x16x32_bf16 v[26:29], v[86:89], v[190:193], v[26:29]
	v_mfma_f32_16x16x32_bf16 v[14:17], v[54:57], v[198:201], v[14:17]
	v_mfma_f32_16x16x32_bf16 v[10:13], v[86:89], v[198:201], v[10:13]
	s_barrier
	s_add_u32 s36, s36, 0x40080
	s_addc_u32 s37, s37, 0
	s_add_i32 s52, s52, s26
	v_lshl_add_u64 v[50:51], s[36:37], 0, v[180:181]
	s_mov_b32 m0, s52
	s_nop 0
	global_load_lds_dwordx4 v[50:51], off
	v_lshl_add_u64 v[50:51], s[36:37], 0, v[176:177]
	s_add_i32 m0, s52, 0x2000
	s_nop 0
	global_load_lds_dwordx4 v[50:51], off
	s_waitcnt vmcnt(6)
	s_barrier
	v_mfma_f32_16x16x32_bf16 v[42:45], v[206:209], v[58:61], v[42:45]
	v_mfma_f32_16x16x32_bf16 v[86:89], v[210:213], v[62:65], v[42:45]
	v_mfma_f32_16x16x32_bf16 v[42:45], v[214:217], v[58:61], v[46:49]
	v_mfma_f32_16x16x32_bf16 v[34:37], v[206:209], v[70:73], v[34:37]
	v_mfma_f32_16x16x32_bf16 v[38:41], v[214:217], v[70:73], v[38:41]
	v_mfma_f32_16x16x32_bf16 v[18:21], v[206:209], v[172:175], v[18:21]
	v_mfma_f32_16x16x32_bf16 v[22:25], v[214:217], v[172:175], v[22:25]
	v_mfma_f32_16x16x32_bf16 v[2:5], v[206:209], v[194:197], v[2:5]
	v_mfma_f32_16x16x32_bf16 v[6:9], v[214:217], v[194:197], v[6:9]
	v_mfma_f32_16x16x32_bf16 v[82:85], v[218:221], v[62:65], v[42:45]
	v_mfma_f32_16x16x32_bf16 v[34:37], v[210:213], v[74:77], v[34:37]
	v_mfma_f32_16x16x32_bf16 v[38:41], v[218:221], v[74:77], v[38:41]
	v_mfma_f32_16x16x32_bf16 v[18:21], v[210:213], v[190:193], v[18:21]
	v_mfma_f32_16x16x32_bf16 v[22:25], v[218:221], v[190:193], v[22:25]
	v_mfma_f32_16x16x32_bf16 v[2:5], v[210:213], v[198:201], v[2:5]
	v_mfma_f32_16x16x32_bf16 v[6:9], v[218:221], v[198:201], v[6:9]
	s_add_i32 s24, s24, 2
	s_add_u32 s0, s0, 0x100
	s_addc_u32 s1, s1, 0
	s_add_u32 vcc_lo, vcc_lo, 0x100
	s_addc_u32 vcc_hi, vcc_hi, 0
	s_cmp_gt_u32 s24, 13
	s_barrier
	s_cbranch_scc0 .LBB0_211
	s_setprio 0
	s_lshl_b32 s2, s2, 8
	s_add_i32 s2, s2, s71
	v_lshl_or_b32 v190, s3, 7, v241
	v_or_b32_e32 v196, s2, v168
	v_ashrrev_i32_e32 v191, 31, v190
	v_ashrrev_i32_e32 v197, 31, v196
	s_and_b32 s24, s95, 1
	s_lshl_b32 s24, s24, 12
	s_add_i32 s24, s24, 0x20400
	v_lshl_add_u32 v173, v241, 2, s24
	v_add_lshl_u32 v172, s71, v168, 3
	v_add_u32_e32 v172, s24, v172
	ds_read_b128 v[42:45], v173
	ds_read_b128 v[58:61], v173 offset:16
	ds_read_b128 v[46:49], v173 offset:512
	ds_read_b128 v[62:65], v173 offset:528
	ds_read_b128 v[50:53], v173 offset:1024
	ds_read_b128 v[70:73], v173 offset:1040
	ds_read_b128 v[54:57], v173 offset:1536
	ds_read_b128 v[74:77], v173 offset:1552
	ds_read_b64 v[174:175], v172 offset:2048
	ds_read_b64 v[206:207], v172 offset:2176
	ds_read_b64 v[204:205], v172 offset:2304
	ds_read_b64 v[202:203], v172 offset:2432
	ds_read_b64 v[200:201], v172 offset:3072
	ds_read_b64 v[198:199], v172 offset:3200
	ds_read_b64 v[194:195], v172 offset:3328
	ds_read_b64 v[192:193], v172 offset:3456
	v_mov_b32_e32 v217, v1
	v_mov_b32_e32 v219, v1
	s_waitcnt lgkmcnt(0)
	v_ffbh_u32_e32 v0, v175
	v_min_u32_e32 v0, 32, v0
	v_lshlrev_b64 v[172:173], v0, v[174:175]
	v_min_u32_e32 v172, 1, v172
	v_or_b32_e32 v172, v173, v172
	v_cvt_f32_u32_e32 v172, v172
	v_sub_u32_e32 v0, 32, v0
	v_mov_b32_dpp v217, v217 row_ror:1 row_mask:0xf bank_mask:0xf
	v_mov_b32_dpp v219, v219 row_ror:2 row_mask:0xf bank_mask:0xf
	v_ldexp_f32 v0, v172, v0
	v_fmamk_f32 v0, v0, 0x30800000, v162
	v_cmp_gt_f32_e32 vcc, s79, v0
	v_mul_f32_e32 v172, 0x4b800000, v0
	v_mov_b32_e32 v212, v217
	v_cndmask_b32_e32 v0, v0, v172, vcc
	v_rsq_f32_e32 v0, v0
	v_mov_b32_e32 v213, v217
	v_mov_b32_e32 v214, v219
	v_mov_b32_e32 v215, v219
	v_mul_f32_e32 v172, 0x45800000, v0
	v_cndmask_b32_e32 v0, v0, v172, vcc
	v_pk_mul_f32 v[158:159], v[158:159], v[0:1] op_sel_hi:[1,0]
	v_pk_mul_f32 v[154:155], v[154:155], v[0:1] op_sel_hi:[1,0]
	v_pk_mul_f32 v[208:209], v[150:151], v[0:1] op_sel_hi:[1,0]
	v_pk_mul_f32 v[210:211], v[146:147], v[0:1] op_sel_hi:[1,0]
	v_pk_mul_f32 v[150:151], v[160:161], v[0:1] op_sel_hi:[1,0]
	v_pk_mul_f32 v[146:147], v[156:157], v[0:1] op_sel_hi:[1,0]
	v_mov_b32_e32 v156, v217
	v_mov_b32_e32 v157, v217
	v_mov_b32_e32 v160, v219
	v_mov_b32_e32 v161, v219
	v_mov_b32_e32 v220, v217
	v_mov_b32_e32 v221, v217
	v_mov_b32_e32 v222, v219
	v_mov_b32_e32 v223, v219
	v_mov_b32_e32 v216, v217
	v_mov_b32_e32 v218, v219
	v_pk_mul_f32 v[152:153], v[152:153], v[0:1] op_sel_hi:[1,0]
	v_pk_mul_f32 v[148:149], v[148:149], v[0:1] op_sel_hi:[1,0]
	v_mov_b32_dpp v156, v158 row_shr:1 row_mask:0xf bank_mask:0xf
	v_mov_b32_dpp v157, v159 row_shr:1 row_mask:0xf bank_mask:0xf
	v_mov_b32_dpp v160, v158 row_shr:2 row_mask:0xf bank_mask:0xf
	v_mov_b32_dpp v161, v159 row_shr:2 row_mask:0xf bank_mask:0xf
	v_mov_b32_dpp v212, v150 row_shr:1 row_mask:0xf bank_mask:0xf
	v_mov_b32_dpp v213, v151 row_shr:1 row_mask:0xf bank_mask:0xf
	v_mov_b32_dpp v214, v150 row_shr:2 row_mask:0xf bank_mask:0xf
	v_mov_b32_dpp v215, v151 row_shr:2 row_mask:0xf bank_mask:0xf
	v_mov_b32_dpp v220, v154 row_shr:1 row_mask:0xf bank_mask:0xf
	v_mov_b32_dpp v221, v155 row_shr:1 row_mask:0xf bank_mask:0xf
	v_mov_b32_dpp v222, v154 row_shr:2 row_mask:0xf bank_mask:0xf
	v_mov_b32_dpp v223, v155 row_shr:2 row_mask:0xf bank_mask:0xf
	v_mov_b32_dpp v216, v146 row_shr:1 row_mask:0xf bank_mask:0xf
	v_mov_b32_dpp v217, v147 row_shr:1 row_mask:0xf bank_mask:0xf
	v_mov_b32_dpp v218, v146 row_shr:2 row_mask:0xf bank_mask:0xf
	v_mov_b32_dpp v219, v147 row_shr:2 row_mask:0xf bank_mask:0xf
	s_and_saveexec_b64 s[0:1], s[40:41]
	s_xor_b64 s[0:1], exec, s[0:1]
	s_cbranch_execz .LBB0_214
; __device__ __forceinline__ u32x4 pack8(const float* f) { u32x4 w; w.x = pk2(f[0], f[1]); w.y = pk2(f[2], f[3]); w.z = pk2(f[4], f[5]); w.w = pk2(f[6], f[7]); return w; }
; template <int N> __device__ __forceinline__ float dpp_shr(float old, float src) { return __int_as_float(__builtin_amdgcn_update_dpp(__float_as_int(old), __float_as_int(src), 0x110 + N, 0xf, 0xf, false)); }
; template <int N> __device__ __forceinline__ float dpp_ror(float src) { return __int_as_float(__builtin_amdgcn_update_dpp(0, __float_as_int(src), 0x120 + N, 0xf, 0xf, false)); }
;     __device__ __forceinline__ void operator()(const f32x4 (&acc)[2][2][4][2], const Unit& u, int wr, int wc, int fr, int fq) const {
;     ...
;                 for (int e2 = 0; e2 < 4; ++e2) {
;                     const int e = 2 * e2;
;                     const f32x2 gv = {g[e], g[e + 1]};
;                     const f32x2 g1v = {dpp_shr<1>(dpp_ror<1>(gp[e]), g[e]), dpp_shr<1>(dpp_ror<1>(gp[e + 1]), g[e + 1])};
;                     const f32x2 g2v = {dpp_shr<2>(dpp_ror<2>(gp[e]), g[e]), dpp_shr<2>(dpp_ror<2>(gp[e + 1]), g[e + 1])};
;                     const f32x2 w0v = {w0[e], w0[e + 1]}, w1v = {w1[e], w1[e + 1]}, w2v = {w2[e], w2[e + 1]}, bbv = {bb[e], bb[e + 1]}, upv = {up[e], up[e + 1]};
;                     const f32x2 y = __builtin_elementwise_fma(w0v, g2v, __builtin_elementwise_fma(w1v, g1v, __builtin_elementwise_fma(w2v, gv, bbv)));
;                     const f32x2 z = y * __builtin_elementwise_fma(y * y, (f32x2){0.1029432397f, 0.1029432397f}, (f32x2){2.302208198f, 2.302208198f});
;                     f32x2 d; d.x = __builtin_amdgcn_exp2f(z.x); d.y = __builtin_amdgcn_exp2f(z.y);
;                     d = d + 1.0f;
;                     f32x2 r; r.x = __builtin_amdgcn_rcpf(d.x); r.y = __builtin_amdgcn_rcpf(d.y);
;                     const f32x2 ov = __builtin_elementwise_fma(-y, r, y) * upv;
;                     o[e] = ov.x; o[e + 1] = ov.y;
;                 }
;                 if (m == 0 && fr < 2) {
;                     const size_t so = ((size_t)(row >> 6) * 2 + fr) * DFF + f0;
;                     *(u32x4*)(gs01 + so) = pack8(g); *(u32x4*)(us01 + so) = pack8(up);
;                 } else *(u32x4*)(act + (size_t)row * DFF + f0) = pack8(o);
	v_pk_fma_f32 v[172:173], v[72:73], v[146:147], v[76:77]
	s_mov_b32 s24, 0x40135761
	v_pk_fma_f32 v[172:173], v[64:65], v[216:217], v[172:173]
	v_mov_b64_e32 v[216:217], s[24:25]
	v_pk_fma_f32 v[172:173], v[60:61], v[218:219], v[172:173]
	s_mov_b32 s24, 0x3dd2d3e8
	v_pk_mul_f32 v[174:175], v[172:173], v[172:173]
	v_readlane_b32 s36, v252, 57
	v_pk_fma_f32 v[174:175], v[174:175], s[24:25], v[216:217] op_sel_hi:[1,0,0]
	v_readlane_b32 s37, v252, 58
	v_pk_mul_f32 v[174:175], v[172:173], v[174:175]
	s_movk_i32 s3, 0x1600
	v_exp_f32_e32 v174, v174
	v_exp_f32_e32 v175, v175
	s_nop 0
	v_pk_add_f32 v[174:175], v[174:175], 1.0 op_sel_hi:[1,0]
	s_nop 0
	v_rcp_f32_e32 v174, v174
	v_rcp_f32_e32 v175, v175
	s_nop 0
	v_pk_fma_f32 v[172:173], v[172:173], v[174:175], v[172:173] neg_lo:[1,0,0] neg_hi:[1,0,0]
	s_nop 0
	v_pk_mul_f32 v[148:149], v[148:149], v[172:173]
	v_pk_fma_f32 v[172:173], v[70:71], v[154:155], v[74:75]
	s_nop 0
	v_pk_fma_f32 v[172:173], v[62:63], v[220:221], v[172:173]
	s_nop 0
	v_pk_fma_f32 v[172:173], v[58:59], v[222:223], v[172:173]
	s_nop 0
	v_pk_mul_f32 v[174:175], v[172:173], v[172:173]
	s_nop 0
	v_pk_fma_f32 v[174:175], v[174:175], s[24:25], v[216:217] op_sel_hi:[1,0,0]
	s_nop 0
	v_pk_mul_f32 v[174:175], v[172:173], v[174:175]
	s_nop 0
	v_exp_f32_e32 v174, v174
	v_exp_f32_e32 v175, v175
	s_nop 0
	v_pk_add_f32 v[174:175], v[174:175], 1.0 op_sel_hi:[1,0]
	s_nop 0
	v_rcp_f32_e32 v174, v174
	v_rcp_f32_e32 v175, v175
	s_nop 0
	v_pk_fma_f32 v[172:173], v[172:173], v[174:175], v[172:173] neg_lo:[1,0,0] neg_hi:[1,0,0]
	s_nop 0
	v_pk_mul_f32 v[174:175], v[210:211], v[172:173]
	v_pk_fma_f32 v[172:173], v[52:53], v[150:151], v[56:57]
	s_nop 0
	v_pk_fma_f32 v[172:173], v[48:49], v[212:213], v[172:173]
	s_nop 0
	v_pk_fma_f32 v[172:173], v[44:45], v[214:215], v[172:173]
	s_nop 0
	v_pk_mul_f32 v[210:211], v[172:173], v[172:173]
	s_nop 0
	v_pk_fma_f32 v[210:211], v[210:211], s[24:25], v[216:217] op_sel_hi:[1,0,0]
	s_nop 0
	v_pk_mul_f32 v[210:211], v[172:173], v[210:211]
	s_nop 0
	v_exp_f32_e32 v210, v210
	v_exp_f32_e32 v211, v211
	s_nop 0
	v_pk_add_f32 v[210:211], v[210:211], 1.0 op_sel_hi:[1,0]
	s_nop 0
	v_rcp_f32_e32 v210, v210
	v_rcp_f32_e32 v211, v211
	s_nop 0
	v_pk_fma_f32 v[172:173], v[172:173], v[210:211], v[172:173] neg_lo:[1,0,0] neg_hi:[1,0,0]
	s_nop 0
	v_pk_mul_f32 v[152:153], v[152:153], v[172:173]
	v_pk_fma_f32 v[172:173], v[50:51], v[158:159], v[54:55]
	s_nop 0
	v_pk_fma_f32 v[156:157], v[46:47], v[156:157], v[172:173]
	s_nop 0
	v_pk_fma_f32 v[156:157], v[42:43], v[160:161], v[156:157]
	s_nop 0
	v_pk_mul_f32 v[160:161], v[156:157], v[156:157]
	s_nop 0
	v_pk_fma_f32 v[160:161], v[160:161], s[24:25], v[216:217] op_sel_hi:[1,0,0]
	s_nop 0
	v_pk_mul_f32 v[160:161], v[156:157], v[160:161]
	s_nop 0
	v_exp_f32_e32 v160, v160
	v_exp_f32_e32 v161, v161
	s_nop 0
	v_pk_add_f32 v[160:161], v[160:161], 1.0 op_sel_hi:[1,0]
	s_nop 0
	v_rcp_f32_e32 v160, v160
	v_rcp_f32_e32 v161, v161
	s_nop 0
	v_pk_fma_f32 v[156:157], v[156:157], v[160:161], v[156:157] neg_lo:[1,0,0] neg_hi:[1,0,0]
	s_nop 0
	v_pk_mul_f32 v[156:157], v[208:209], v[156:157]
	s_nop 0
	v_cvt_pk_bf16_f32 v172, v156, v157
	v_cvt_pk_bf16_f32 v173, v152, v153
	v_cvt_pk_bf16_f32 v174, v174, v175
	v_cvt_pk_bf16_f32 v175, v148, v149
	v_mov_b64_e32 v[148:149], s[36:37]
	v_mad_i64_i32 v[148:149], s[36:37], v196, s3, v[148:149]
	v_lshl_add_u64 v[148:149], v[190:191], 1, v[148:149]
	global_store_dwordx4 v[148:149], v[172:175], off nt

; #define PG8_STAGE(bufoff, gbase, voff) do { _Pragma("unroll") for (int _i = 0; _i < 2; ++_i) \
;         __builtin_amdgcn_global_load_lds((const unsigned*)((const char*)(gbase) + (voff)[_i]), (LAS unsigned*)(lds + (bufoff) + ldsw + _i * 8192), 16, 0, 0); } while (0)
; #define PG8_LDA(dst, b, h) do { _Pragma("unroll") for (int m = 0; m < 4; ++m) _Pragma("unroll") for (int k = 0; k < 2; ++k) dst[m][k] = *(const LAS bf16x8*)(lds + PG8_SA(b, h) + aoff + m * 2048 + k * 1024); } while (0)
; #define PG8_LDB(dst, b, h) do { _Pragma("unroll") for (int n = 0; n < 2; ++n) _Pragma("unroll") for (int k = 0; k < 2; ++k) dst[n][k] = *(const LAS bf16x8*)(lds + PG8_SB(b, h) + boff + n * 2048 + k * 1024); } while (0)
; #define PG8_MMA(ai, bj, At, Bt) do { __builtin_amdgcn_s_setprio(1); _Pragma("unroll") for (int m = 0; m < 4; ++m) _Pragma("unroll") for (int n = 0; n < 2; ++n) _Pragma("unroll") for (int k = 0; k < 2; ++k) \
;         acc[ai][bj][m][n] = __builtin_amdgcn_mfma_f32_16x16x32_bf16(Bt[n][k], At[m][k], acc[ai][bj][m][n], 0, 0, 0); __builtin_amdgcn_s_setprio(0); } while (0)
; #define PG8_WAIT_L(n) asm volatile("s_waitcnt lgkmcnt(" #n ")" ::: "memory")
; template <class Epi>
; __device__ __forceinline__ void gemm_phase(LAS unsigned char* lds, const Gemm g, const StaticOrder& S, const Epi& E) {
;     ...
;     for (;;) {
;         const bool has_next = S.next(ui + 1, nxt);
;         const char* nA = has_next ? (const char*)g.A + (size_t)nxt.pm * tstep : cA; const char* nB = has_next ? (const char*)g.Bt + (size_t)nxt.pn * tstep : cB;
;         for (int t = 0; t < nt; t += 2) {
;             const bool last = (t == nt - 2);
;             const char* a1 = cA + (size_t)(t + 1) * kstep;
;             const char* a2 = last ? nA : cA + (size_t)(t + 2) * kstep; const char* b2 = last ? nB : cB + (size_t)(t + 2) * kstep;
;             const char* a3 = a2 + kstep; const char* b3 = b2 + kstep;
;             PG8_LDB(B0, 0, 0); PG8_SCHED; PG8_LDA(At, 0, 0); PG8_STAGE(PG8_SA(1, 1), a1 + hstep, voffA);
;             PG8_WAIT_L(8); PG8_BAR; PG8_WAIT_L(0); PG8_MMA(0, 0, At, B0); PG8_BAR; PG8_SCHED;
;             PG8_LDB(B1, 0, 1); PG8_STAGE(PG8_SB(0, 0), b2, voffB);
;             PG8_BAR; PG8_WAIT_L(0); PG8_MMA(0, 1, At, B1); PG8_BAR;
;             PG8_LDA(At, 0, 1); PG8_STAGE(PG8_SA(0, 0), a2, voffA);
;             PG8_BAR; PG8_WAIT_L(0); PG8_MMA(1, 0, At, B0); PG8_BAR; PG8_SCHED;
.LBB0_257:
	s_add_u32 s68, s50, 0x100
	s_addc_u32 s69, s51, 0
	s_add_u32 s46, s48, 0x60080
	s_addc_u32 s47, s49, 0
	v_lshl_add_u64 v[136:137], s[46:47], 0, v[132:133]
	v_lshl_add_u64 v[138:139], s[46:47], 0, v[134:135]
	s_mov_b32 s70, -2
	s_mov_b64 s[50:51], 0
	s_cmpk_gt_u32 s30, 0xff
	s_cbranch_scc0 .Lprio_258
	s_setprio 1
.Lprio_258:
.LBB0_258:
	s_add_u32 s46, s48, s50
	s_addc_u32 s47, s49, s51
	s_add_u32 s46, s46, 0x100
	s_addc_u32 s47, s47, 0
	s_add_u32 s52, s68, s50
	s_addc_u32 s53, s69, s51
	s_add_i32 s71, 0, 0x10000
	v_add_u32_e32 v140, s71, v143
	ds_read_b128 v[148:151], v140
	ds_read_b128 v[152:155], v140 offset:1024
	ds_read_b128 v[156:159], v140 offset:2048
	ds_read_b128 v[172:175], v140 offset:3072
	s_cmpk_eq_i32 s50, 0xb00
	s_cselect_b32 s47, s37, s47
	s_cselect_b32 s46, s36, s46
	s_cselect_b32 s53, s45, s53
	s_cselect_b32 s52, s44, s52
	v_lshl_add_u64 v[140:141], v[136:137], 0, s[50:51]
	s_add_i32 m0, s55, 0xc000
	ds_read_b128 v[178:181], v147
	ds_read_b128 v[182:185], v147 offset:1024
	ds_read_b128 v[186:189], v147 offset:2048
	ds_read_b128 v[190:193], v147 offset:3072
	ds_read_b128 v[194:197], v147 offset:4096
	ds_read_b128 v[198:201], v147 offset:5120
	ds_read_b128 v[202:205], v147 offset:6144
	ds_read_b128 v[206:209], v147 offset:7168
	global_load_lds_dwordx4 v[140:141], off
	v_lshl_add_u64 v[140:141], v[138:139], 0, s[50:51]
	s_add_i32 m0, s55, 0xe000
	s_nop 0
	global_load_lds_dwordx4 v[140:141], off
	s_waitcnt lgkmcnt(8)
	s_barrier
	s_waitcnt lgkmcnt(0)
	s_waitcnt lgkmcnt(0)
	v_mfma_f32_16x16x32_bf16 v[126:129], v[148:151], v[178:181], v[126:129]
	v_mfma_f32_16x16x32_bf16 v[122:125], v[156:159], v[178:181], v[122:125]
	v_mfma_f32_16x16x32_bf16 v[110:113], v[148:151], v[186:189], v[110:113]
	v_mfma_f32_16x16x32_bf16 v[106:109], v[156:159], v[186:189], v[106:109]
	v_mfma_f32_16x16x32_bf16 v[94:97], v[148:151], v[194:197], v[94:97]
	v_mfma_f32_16x16x32_bf16 v[90:93], v[156:159], v[194:197], v[90:93]
	v_mfma_f32_16x16x32_bf16 v[78:81], v[148:151], v[202:205], v[78:81]
	v_mfma_f32_16x16x32_bf16 v[74:77], v[156:159], v[202:205], v[74:77]
	v_mfma_f32_16x16x32_bf16 v[126:129], v[152:155], v[182:185], v[126:129]
	v_mfma_f32_16x16x32_bf16 v[122:125], v[172:175], v[182:185], v[122:125]
	v_mfma_f32_16x16x32_bf16 v[110:113], v[152:155], v[190:193], v[110:113]
	v_mfma_f32_16x16x32_bf16 v[106:109], v[172:175], v[190:193], v[106:109]
	v_mfma_f32_16x16x32_bf16 v[94:97], v[152:155], v[198:201], v[94:97]
	v_mfma_f32_16x16x32_bf16 v[90:93], v[172:175], v[198:201], v[90:93]
	v_mfma_f32_16x16x32_bf16 v[78:81], v[152:155], v[206:209], v[78:81]
	v_mfma_f32_16x16x32_bf16 v[74:77], v[172:175], v[206:209], v[74:77]
	s_barrier
	s_add_i32 s93, 0, 0x14000
	v_add_u32_e32 v140, s93, v143
	s_add_i32 s71, s71, s54
	ds_read_b128 v[210:213], v140
	ds_read_b128 v[214:217], v140 offset:1024
	ds_read_b128 v[218:221], v140 offset:2048
	ds_read_b128 v[246:249], v140 offset:3072
	v_lshl_add_u64 v[140:141], s[52:53], 0, v[0:1]
	s_mov_b32 m0, s71
	v_lshl_add_u64 v[160:161], s[52:53], 0, v[130:131]
	global_load_lds_dwordx4 v[140:141], off
	s_add_i32 m0, s71, 0x2000
	s_nop 0
	global_load_lds_dwordx4 v[160:161], off
	s_barrier
	s_waitcnt lgkmcnt(0)
	s_waitcnt lgkmcnt(0)
	v_mfma_f32_16x16x32_bf16 v[118:121], v[210:213], v[178:181], v[118:121]
	v_mfma_f32_16x16x32_bf16 v[114:117], v[218:221], v[178:181], v[114:117]
	v_mfma_f32_16x16x32_bf16 v[102:105], v[210:213], v[186:189], v[102:105]
	v_mfma_f32_16x16x32_bf16 v[98:101], v[218:221], v[186:189], v[98:101]
	v_mfma_f32_16x16x32_bf16 v[86:89], v[210:213], v[194:197], v[86:89]
	v_mfma_f32_16x16x32_bf16 v[82:85], v[218:221], v[194:197], v[82:85]
	v_mfma_f32_16x16x32_bf16 v[70:73], v[210:213], v[202:205], v[70:73]
	v_mfma_f32_16x16x32_bf16 v[66:69], v[218:221], v[202:205], v[66:69]
	v_mfma_f32_16x16x32_bf16 v[118:121], v[214:217], v[182:185], v[118:121]
	v_mfma_f32_16x16x32_bf16 v[114:117], v[246:249], v[182:185], v[114:117]
	v_mfma_f32_16x16x32_bf16 v[102:105], v[214:217], v[190:193], v[102:105]
	v_mfma_f32_16x16x32_bf16 v[98:101], v[246:249], v[190:193], v[98:101]
	v_mfma_f32_16x16x32_bf16 v[86:89], v[214:217], v[198:201], v[86:89]
	v_mfma_f32_16x16x32_bf16 v[82:85], v[246:249], v[198:201], v[82:85]
	v_mfma_f32_16x16x32_bf16 v[70:73], v[214:217], v[206:209], v[70:73]
	v_mfma_f32_16x16x32_bf16 v[66:69], v[246:249], v[206:209], v[66:69]
	s_mov_b32 m0, s55
	v_lshl_add_u64 v[222:223], s[46:47], 0, v[0:1]
	s_barrier
	ds_read_b128 v[178:181], v147 offset:16384
	ds_read_b128 v[182:185], v147 offset:17408
	ds_read_b128 v[186:189], v147 offset:18432
	ds_read_b128 v[190:193], v147 offset:19456
	ds_read_b128 v[194:197], v147 offset:20480
	ds_read_b128 v[198:201], v147 offset:21504
	ds_read_b128 v[202:205], v147 offset:22528
	ds_read_b128 v[206:209], v147 offset:23552
	global_load_lds_dwordx4 v[222:223], off
	v_lshl_add_u64 v[242:243], s[46:47], 0, v[130:131]
	s_mov_b32 m0, s58
	s_nop 0
	global_load_lds_dwordx4 v[242:243], off
	s_barrier
	s_waitcnt lgkmcnt(0)
	s_waitcnt lgkmcnt(0)
	v_mfma_f32_16x16x32_bf16 v[62:65], v[148:151], v[178:181], v[62:65]
	v_mfma_f32_16x16x32_bf16 v[58:61], v[156:159], v[178:181], v[58:61]
	v_mfma_f32_16x16x32_bf16 v[46:49], v[148:151], v[186:189], v[46:49]
	v_mfma_f32_16x16x32_bf16 v[42:45], v[156:159], v[186:189], v[42:45]
	v_mfma_f32_16x16x32_bf16 v[30:33], v[148:151], v[194:197], v[30:33]
	v_mfma_f32_16x16x32_bf16 v[26:29], v[156:159], v[194:197], v[26:29]
	v_mfma_f32_16x16x32_bf16 v[14:17], v[148:151], v[202:205], v[14:17]
	v_mfma_f32_16x16x32_bf16 v[10:13], v[156:159], v[202:205], v[10:13]
	v_mfma_f32_16x16x32_bf16 v[62:65], v[152:155], v[182:185], v[62:65]
	v_mfma_f32_16x16x32_bf16 v[58:61], v[172:175], v[182:185], v[58:61]
	v_mfma_f32_16x16x32_bf16 v[46:49], v[152:155], v[190:193], v[46:49]
	v_mfma_f32_16x16x32_bf16 v[42:45], v[172:175], v[190:193], v[42:45]
	v_mfma_f32_16x16x32_bf16 v[30:33], v[152:155], v[198:201], v[30:33]
	v_mfma_f32_16x16x32_bf16 v[26:29], v[172:175], v[198:201], v[26:29]
	v_mfma_f32_16x16x32_bf16 v[14:17], v[152:155], v[206:209], v[14:17]
	v_mfma_f32_16x16x32_bf16 v[10:13], v[172:175], v[206:209], v[10:13]
	s_barrier
; #define PG8_STAGE(bufoff, gbase, voff) do { _Pragma("unroll") for (int _i = 0; _i < 2; ++_i) \
;         __builtin_amdgcn_global_load_lds((const unsigned*)((const char*)(gbase) + (voff)[_i]), (LAS unsigned*)(lds + (bufoff) + ldsw + _i * 8192), 16, 0, 0); } while (0)
; #define PG8_LDA(dst, b, h) do { _Pragma("unroll") for (int m = 0; m < 4; ++m) _Pragma("unroll") for (int k = 0; k < 2; ++k) dst[m][k] = *(const LAS bf16x8*)(lds + PG8_SA(b, h) + aoff + m * 2048 + k * 1024); } while (0)
; #define PG8_LDB(dst, b, h) do { _Pragma("unroll") for (int n = 0; n < 2; ++n) _Pragma("unroll") for (int k = 0; k < 2; ++k) dst[n][k] = *(const LAS bf16x8*)(lds + PG8_SB(b, h) + boff + n * 2048 + k * 1024); } while (0)
; #define PG8_MMA(ai, bj, At, Bt) do { __builtin_amdgcn_s_setprio(1); _Pragma("unroll") for (int m = 0; m < 4; ++m) _Pragma("unroll") for (int n = 0; n < 2; ++n) _Pragma("unroll") for (int k = 0; k < 2; ++k) \
;         acc[ai][bj][m][n] = __builtin_amdgcn_mfma_f32_16x16x32_bf16(Bt[n][k], At[m][k], acc[ai][bj][m][n], 0, 0, 0); __builtin_amdgcn_s_setprio(0); } while (0)
; #define PG8_WAIT_V(n) asm volatile("s_waitcnt vmcnt(" #n ")" ::: "memory")
; #define PG8_WAIT_L(n) asm volatile("s_waitcnt lgkmcnt(" #n ")" ::: "memory")
; #define PG8_BAR __builtin_amdgcn_s_barrier()
; #define PG8_SCHED __builtin_amdgcn_sched_barrier(0)
; template <class Epi>
; __device__ __forceinline__ void gemm_phase(LAS unsigned char* lds, const Gemm g, const StaticOrder& S, const Epi& E) {
;     ...
;             PG8_STAGE(PG8_SB(0, 1), b2 + hstep, voffB);
;             PG8_WAIT_V(6); PG8_BAR; PG8_MMA(1, 1, At, B1); PG8_BAR;
;             PG8_LDB(B0, 1, 0); PG8_SCHED; PG8_LDA(At, 1, 0); PG8_STAGE(PG8_SA(0, 1), a2 + hstep, voffA);
;             PG8_WAIT_L(8); PG8_BAR; PG8_WAIT_L(0); PG8_MMA(0, 0, At, B0); PG8_BAR; PG8_SCHED;
;             PG8_LDB(B1, 1, 1); PG8_STAGE(PG8_SB(1, 0), b3, voffB);
;             PG8_BAR; PG8_WAIT_L(0); PG8_MMA(0, 1, At, B1); PG8_BAR;
;             PG8_LDA(At, 1, 1); PG8_STAGE(PG8_SA(1, 0), a3, voffA);
;             PG8_BAR; PG8_WAIT_L(0); PG8_MMA(1, 0, At, B0); PG8_BAR; PG8_SCHED;
	s_add_u32 s94, s52, 0x60000
	s_addc_u32 s95, s53, 0
	s_add_i32 s71, s93, s54
	v_lshl_add_u64 v[148:149], s[94:95], 0, v[0:1]
	s_mov_b32 m0, s71
	s_nop 0
	global_load_lds_dwordx4 v[148:149], off
	v_lshl_add_u64 v[148:149], s[94:95], 0, v[130:131]
	s_add_i32 m0, s71, 0x2000
	s_nop 0
	global_load_lds_dwordx4 v[148:149], off
	s_waitcnt vmcnt(6)
	s_barrier
	v_mfma_f32_16x16x32_bf16 v[54:57], v[210:213], v[178:181], v[54:57]
	v_mfma_f32_16x16x32_bf16 v[50:53], v[218:221], v[178:181], v[50:53]
	v_mfma_f32_16x16x32_bf16 v[38:41], v[210:213], v[186:189], v[38:41]
	v_mfma_f32_16x16x32_bf16 v[34:37], v[218:221], v[186:189], v[34:37]
	v_mfma_f32_16x16x32_bf16 v[22:25], v[210:213], v[194:197], v[22:25]
	v_mfma_f32_16x16x32_bf16 v[18:21], v[218:221], v[194:197], v[18:21]
	v_mfma_f32_16x16x32_bf16 v[6:9], v[210:213], v[202:205], v[6:9]
	v_mfma_f32_16x16x32_bf16 v[2:5], v[218:221], v[202:205], v[2:5]
	v_mfma_f32_16x16x32_bf16 v[54:57], v[214:217], v[182:185], v[54:57]
	v_mfma_f32_16x16x32_bf16 v[50:53], v[246:249], v[182:185], v[50:53]
	v_mfma_f32_16x16x32_bf16 v[38:41], v[214:217], v[190:193], v[38:41]
	v_mfma_f32_16x16x32_bf16 v[34:37], v[246:249], v[190:193], v[34:37]
	v_mfma_f32_16x16x32_bf16 v[22:25], v[214:217], v[198:201], v[22:25]
	v_mfma_f32_16x16x32_bf16 v[18:21], v[246:249], v[198:201], v[18:21]
	v_mfma_f32_16x16x32_bf16 v[6:9], v[214:217], v[206:209], v[6:9]
	v_mfma_f32_16x16x32_bf16 v[2:5], v[246:249], v[206:209], v[2:5]
	s_add_i32 s71, 0, 0x18000
	v_add_u32_e32 v172, s71, v143
	s_barrier
	ds_read_b128 v[148:151], v172
	ds_read_b128 v[152:155], v172 offset:1024
	ds_read_b128 v[156:159], v172 offset:2048
	ds_read_b128 v[172:175], v172 offset:3072
	s_add_u32 s46, s46, 0x60000
	s_addc_u32 s47, s47, 0
	s_mov_b32 m0, s59
	v_lshl_add_u64 v[210:211], s[46:47], 0, v[0:1]
	ds_read_b128 v[178:181], v147 offset:32768
	ds_read_b128 v[182:185], v147 offset:33792
	ds_read_b128 v[186:189], v147 offset:34816
	ds_read_b128 v[190:193], v147 offset:35840
	ds_read_b128 v[194:197], v147 offset:36864
	ds_read_b128 v[198:201], v147 offset:37888
	ds_read_b128 v[202:205], v147 offset:38912
	ds_read_b128 v[206:209], v147 offset:39936
	global_load_lds_dwordx4 v[210:211], off
	v_lshl_add_u64 v[210:211], s[46:47], 0, v[130:131]
	s_mov_b32 m0, s61
	s_nop 0
	global_load_lds_dwordx4 v[210:211], off
	s_waitcnt lgkmcnt(8)
	s_barrier
	s_waitcnt lgkmcnt(0)
	s_waitcnt lgkmcnt(0)
	v_mfma_f32_16x16x32_bf16 v[126:129], v[148:151], v[178:181], v[126:129]
	v_mfma_f32_16x16x32_bf16 v[122:125], v[156:159], v[178:181], v[122:125]
	v_mfma_f32_16x16x32_bf16 v[110:113], v[148:151], v[186:189], v[110:113]
	v_mfma_f32_16x16x32_bf16 v[106:109], v[156:159], v[186:189], v[106:109]
	v_mfma_f32_16x16x32_bf16 v[94:97], v[148:151], v[194:197], v[94:97]
	v_mfma_f32_16x16x32_bf16 v[90:93], v[156:159], v[194:197], v[90:93]
	v_mfma_f32_16x16x32_bf16 v[78:81], v[148:151], v[202:205], v[78:81]
	v_mfma_f32_16x16x32_bf16 v[74:77], v[156:159], v[202:205], v[74:77]
	v_mfma_f32_16x16x32_bf16 v[126:129], v[152:155], v[182:185], v[126:129]
	v_mfma_f32_16x16x32_bf16 v[122:125], v[172:175], v[182:185], v[122:125]
	v_mfma_f32_16x16x32_bf16 v[110:113], v[152:155], v[190:193], v[110:113]
	v_mfma_f32_16x16x32_bf16 v[106:109], v[172:175], v[190:193], v[106:109]
	v_mfma_f32_16x16x32_bf16 v[94:97], v[152:155], v[198:201], v[94:97]
	v_mfma_f32_16x16x32_bf16 v[90:93], v[172:175], v[198:201], v[90:93]
	v_mfma_f32_16x16x32_bf16 v[78:81], v[152:155], v[206:209], v[78:81]
	v_mfma_f32_16x16x32_bf16 v[74:77], v[172:175], v[206:209], v[74:77]
	s_barrier
	s_add_i32 s93, 0, 0x1c000
	s_add_i32 s46, s71, s54
	v_add_u32_e32 v177, s93, v143
	v_lshl_add_u64 v[140:141], v[140:141], 0, s[28:29]
	s_mov_b32 m0, s46
	ds_read_b128 v[210:213], v177
	ds_read_b128 v[214:217], v177 offset:1024
	ds_read_b128 v[218:221], v177 offset:2048
	ds_read_b128 v[246:249], v177 offset:3072
	global_load_lds_dwordx4 v[140:141], off
	v_lshl_add_u64 v[140:141], v[160:161], 0, s[28:29]
	s_add_i32 m0, s46, 0x2000
	s_nop 0
	global_load_lds_dwordx4 v[140:141], off
	s_barrier
	s_waitcnt lgkmcnt(0)
	s_waitcnt lgkmcnt(0)
	v_mfma_f32_16x16x32_bf16 v[118:121], v[210:213], v[178:181], v[118:121]
	v_mfma_f32_16x16x32_bf16 v[114:117], v[218:221], v[178:181], v[114:117]
	v_mfma_f32_16x16x32_bf16 v[102:105], v[210:213], v[186:189], v[102:105]
	v_mfma_f32_16x16x32_bf16 v[98:101], v[218:221], v[186:189], v[98:101]
	v_mfma_f32_16x16x32_bf16 v[86:89], v[210:213], v[194:197], v[86:89]
	v_mfma_f32_16x16x32_bf16 v[82:85], v[218:221], v[194:197], v[82:85]
	v_mfma_f32_16x16x32_bf16 v[70:73], v[210:213], v[202:205], v[70:73]
	v_mfma_f32_16x16x32_bf16 v[66:69], v[218:221], v[202:205], v[66:69]
	v_mfma_f32_16x16x32_bf16 v[118:121], v[214:217], v[182:185], v[118:121]
	v_mfma_f32_16x16x32_bf16 v[114:117], v[246:249], v[182:185], v[114:117]
	v_mfma_f32_16x16x32_bf16 v[102:105], v[214:217], v[190:193], v[102:105]
	v_mfma_f32_16x16x32_bf16 v[98:101], v[246:249], v[190:193], v[98:101]
	v_mfma_f32_16x16x32_bf16 v[86:89], v[214:217], v[198:201], v[86:89]
	v_mfma_f32_16x16x32_bf16 v[82:85], v[246:249], v[198:201], v[82:85]
	v_mfma_f32_16x16x32_bf16 v[70:73], v[214:217], v[206:209], v[70:73]
	v_mfma_f32_16x16x32_bf16 v[66:69], v[246:249], v[206:209], v[66:69]
	s_mov_b32 m0, s62
	v_lshl_add_u64 v[140:141], v[222:223], 0, s[28:29]
	s_barrier
	ds_read_b128 v[178:181], v147 offset:49152
	ds_read_b128 v[182:185], v147 offset:50176
	ds_read_b128 v[186:189], v147 offset:51200
	ds_read_b128 v[190:193], v147 offset:52224
	ds_read_b128 v[194:197], v147 offset:53248
	ds_read_b128 v[198:201], v147 offset:54272
	ds_read_b128 v[202:205], v147 offset:55296
	ds_read_b128 v[206:209], v147 offset:56320
	global_load_lds_dwordx4 v[140:141], off
	v_lshl_add_u64 v[140:141], v[242:243], 0, s[28:29]
	s_mov_b32 m0, s63
	s_nop 0
	global_load_lds_dwordx4 v[140:141], off
	s_barrier
; __device__ __forceinline__ u64 ss_fix(float ss) { return (u64)(ss * 1048576.f + 0.5f); }
; __device__ __forceinline__ unsigned pk2(float lo, float hi) { unsigned r; asm volatile("v_cvt_pk_bf16_f32 %0, %1, %2" : "=v"(r) : "v"(lo), "v"(hi)); return r; }
; __device__ __forceinline__ float shfl_xor_(float v, int o, int lane) { return shfl_idx(v, lane ^ o); }
; #define PG8_STAGE(bufoff, gbase, voff) do { _Pragma("unroll") for (int _i = 0; _i < 2; ++_i) \
;         __builtin_amdgcn_global_load_lds((const unsigned*)((const char*)(gbase) + (voff)[_i]), (LAS unsigned*)(lds + (bufoff) + ldsw + _i * 8192), 16, 0, 0); } while (0)
; #define PG8_WAIT_V(n) asm volatile("s_waitcnt vmcnt(" #n ")" ::: "memory")
; #define PG8_BAR __builtin_amdgcn_s_barrier()
; template <class Epi>
; __device__ __forceinline__ void gemm_phase(LAS unsigned char* lds, const Gemm g, const StaticOrder& S, const Epi& E) {
;     ...
;             PG8_BAR; PG8_WAIT_L(0); PG8_MMA(1, 0, At, B0); PG8_BAR; PG8_SCHED;
;             PG8_STAGE(PG8_SB(1, 1), b3 + hstep, voffB);
;             PG8_WAIT_V(6); PG8_BAR; PG8_MMA(1, 1, At, B1); PG8_BAR;
;         }
;         if constexpr (Epi::AFTER_DRAIN) { if (has_next) E(acc, cur, wr, wc, fr, fq); } else E(acc, cur, wr, wc, fr, fq);
;     __device__ __forceinline__ void operator()(const f32x4 (&acc)[2][2][4][2], const Unit& u, int wr, int wc, int fr, int fq) const {
;         const int row0 = u.pm * BM + wr * 64 + fr, col0 = u.pn * BM + wc * 32 + 4 * fq, lane = fr | (fq << 4);
; #pragma unroll
;         for (int ai = 0; ai < 2; ++ai)
; #pragma unroll
;             for (int m = 0; m < 4; ++m) { const int row = row0 + ai * HALF + m * 16; bf16_t* xbp = xb + (size_t)row * ldc + col0;
;                 float ss = 0.f;
; #pragma unroll
;                 for (int bj = 0; bj < 2; ++bj)
; #pragma unroll
;                     for (int n = 0; n < 2; ++n) { u32x2* pp = (u32x2*)(xbp + bj * HALF + n * 16); float o[4]; unpack4(*pp, o);
;                         u32x2 w; w.x = pk2(o[0] + acc[ai][bj][m][n][0], o[1] + acc[ai][bj][m][n][1]); w.y = pk2(o[2] + acc[ai][bj][m][n][2], o[3] + acc[ai][bj][m][n][3]); *pp = w;
;                         unpack4(w, o); ss += o[0] * o[0] + o[1] * o[1] + o[2] * o[2] + o[3] * o[3]; }
;                 ss += shfl_xor_(ss, 16, lane); ss += shfl_xor_(ss, 32, lane);
;                 if (fq == 0) atomicAdd(rss + row, ss_fix(ss)); }
	s_waitcnt lgkmcnt(0)
	s_waitcnt lgkmcnt(0)
	v_mfma_f32_16x16x32_bf16 v[62:65], v[148:151], v[178:181], v[62:65]
	v_mfma_f32_16x16x32_bf16 v[58:61], v[156:159], v[178:181], v[58:61]
	v_mfma_f32_16x16x32_bf16 v[46:49], v[148:151], v[186:189], v[46:49]
	v_mfma_f32_16x16x32_bf16 v[42:45], v[156:159], v[186:189], v[42:45]
	v_mfma_f32_16x16x32_bf16 v[30:33], v[148:151], v[194:197], v[30:33]
	v_mfma_f32_16x16x32_bf16 v[26:29], v[156:159], v[194:197], v[26:29]
	v_mfma_f32_16x16x32_bf16 v[14:17], v[148:151], v[202:205], v[14:17]
	v_mfma_f32_16x16x32_bf16 v[10:13], v[156:159], v[202:205], v[10:13]
	v_mfma_f32_16x16x32_bf16 v[62:65], v[152:155], v[182:185], v[62:65]
	v_mfma_f32_16x16x32_bf16 v[58:61], v[172:175], v[182:185], v[58:61]
	v_mfma_f32_16x16x32_bf16 v[46:49], v[152:155], v[190:193], v[46:49]
	v_mfma_f32_16x16x32_bf16 v[42:45], v[172:175], v[190:193], v[42:45]
	v_mfma_f32_16x16x32_bf16 v[30:33], v[152:155], v[198:201], v[30:33]
	v_mfma_f32_16x16x32_bf16 v[26:29], v[172:175], v[198:201], v[26:29]
	v_mfma_f32_16x16x32_bf16 v[14:17], v[152:155], v[206:209], v[14:17]
	v_mfma_f32_16x16x32_bf16 v[10:13], v[172:175], v[206:209], v[10:13]
	s_barrier
	s_add_u32 s46, s52, 0x60080
	s_addc_u32 s47, s53, 0
	s_add_i32 s52, s93, s54
	v_lshl_add_u64 v[140:141], s[46:47], 0, v[0:1]
	s_mov_b32 m0, s52
	s_nop 0
	global_load_lds_dwordx4 v[140:141], off
	v_lshl_add_u64 v[140:141], s[46:47], 0, v[130:131]
	s_add_i32 m0, s52, 0x2000
	s_nop 0
	global_load_lds_dwordx4 v[140:141], off
	s_waitcnt vmcnt(6)
	s_barrier
	v_mfma_f32_16x16x32_bf16 v[54:57], v[210:213], v[178:181], v[54:57]
	v_mfma_f32_16x16x32_bf16 v[50:53], v[218:221], v[178:181], v[50:53]
	v_mfma_f32_16x16x32_bf16 v[38:41], v[210:213], v[186:189], v[38:41]
	v_mfma_f32_16x16x32_bf16 v[34:37], v[218:221], v[186:189], v[34:37]
	v_mfma_f32_16x16x32_bf16 v[22:25], v[210:213], v[194:197], v[22:25]
	v_mfma_f32_16x16x32_bf16 v[18:21], v[218:221], v[194:197], v[18:21]
	v_mfma_f32_16x16x32_bf16 v[6:9], v[210:213], v[202:205], v[6:9]
	v_mfma_f32_16x16x32_bf16 v[2:5], v[218:221], v[202:205], v[2:5]
	v_mfma_f32_16x16x32_bf16 v[54:57], v[214:217], v[182:185], v[54:57]
	v_mfma_f32_16x16x32_bf16 v[50:53], v[246:249], v[182:185], v[50:53]
	v_mfma_f32_16x16x32_bf16 v[38:41], v[214:217], v[190:193], v[38:41]
	v_mfma_f32_16x16x32_bf16 v[34:37], v[246:249], v[190:193], v[34:37]
	v_mfma_f32_16x16x32_bf16 v[22:25], v[214:217], v[198:201], v[22:25]
	v_mfma_f32_16x16x32_bf16 v[18:21], v[246:249], v[198:201], v[18:21]
	v_mfma_f32_16x16x32_bf16 v[6:9], v[214:217], v[206:209], v[6:9]
	v_mfma_f32_16x16x32_bf16 v[2:5], v[246:249], v[206:209], v[2:5]
	s_add_i32 s70, s70, 2
	s_add_u32 s50, s50, 0x100
	s_addc_u32 s51, s51, 0
	s_cmp_gt_u32 s70, 21
	s_barrier
	s_cbranch_scc0 .LBB0_258
	s_setprio 0
	s_add_u32 s46, s68, 0xffffff00
	s_addc_u32 s47, s69, -1
	s_and_b64 vcc, exec, s[0:1]
	s_cbranch_vccz .LBB0_277
	v_lshl_add_u32 v140, s66, 8, v142
	v_ashrrev_i32_e32 v141, 31, v140
	v_readlane_b32 s0, v252, 51
	v_lshl_or_b32 v138, s65, 8, v144
	v_lshlrev_b64 v[136:137], 11, v[140:141]
	v_readlane_b32 s1, v252, 52
	v_ashrrev_i32_e32 v139, 31, v138
	s_nop 0
	v_lshl_add_u64 v[136:137], s[0:1], 0, v[136:137]
	v_lshl_add_u64 v[136:137], v[138:139], 1, v[136:137]
	global_load_dwordx2 v[148:149], v[136:137], off
	s_waitcnt vmcnt(0)
	v_lshlrev_b32_e32 v150, 16, v148
	v_and_b32_e32 v148, 0xffff0000, v148
	v_lshlrev_b32_e32 v151, 16, v149
	v_and_b32_e32 v149, 0xffff0000, v149
	v_add_f32_e32 v126, v126, v150
	v_add_f32_e32 v127, v127, v148
	v_add_f32_e32 v128, v128, v151
	v_add_f32_e32 v129, v129, v149
	v_cvt_pk_bf16_f32 v126, v126, v127
	v_cvt_pk_bf16_f32 v127, v128, v129
	global_load_dwordx2 v[128:129], v[136:137], off offset:32
	s_waitcnt vmcnt(0)
	v_lshlrev_b32_e32 v148, 16, v128
	v_and_b32_e32 v128, 0xffff0000, v128
	v_lshlrev_b32_e32 v149, 16, v129
	v_and_b32_e32 v129, 0xffff0000, v129
	v_add_f32_e32 v122, v122, v148
	v_add_f32_e32 v123, v123, v128
	v_add_f32_e32 v124, v124, v149
	v_add_f32_e32 v125, v125, v129
	global_store_dwordx2 v[136:137], v[126:127], off
	v_cvt_pk_bf16_f32 v122, v122, v123
	v_cvt_pk_bf16_f32 v123, v124, v125
	global_load_dwordx2 v[124:125], v[136:137], off offset:256
	s_waitcnt vmcnt(0)
	v_lshlrev_b32_e32 v128, 16, v124
	v_and_b32_e32 v124, 0xffff0000, v124
	v_lshlrev_b32_e32 v129, 16, v125
	v_and_b32_e32 v125, 0xffff0000, v125
	v_add_f32_e32 v118, v118, v128
	v_add_f32_e32 v119, v119, v124
	v_add_f32_e32 v120, v120, v129
	v_add_f32_e32 v121, v121, v125
	global_store_dwordx2 v[136:137], v[122:123], off offset:32
	v_cvt_pk_bf16_f32 v118, v118, v119
	v_cvt_pk_bf16_f32 v119, v120, v121
	global_load_dwordx2 v[120:121], v[136:137], off offset:288
	v_and_b32_e32 v125, 0xffff0000, v126
	v_lshlrev_b32_e32 v124, 16, v126
	v_mul_f32_e32 v125, v125, v125
	v_fmac_f32_e32 v125, v124, v124
	v_lshlrev_b32_e32 v124, 16, v122
	v_and_b32_e32 v122, 0xffff0000, v122
	v_lshlrev_b32_e32 v126, 16, v127
	v_mul_f32_e32 v122, v122, v122
	v_fmac_f32_e32 v125, v126, v126
	v_lshlrev_b32_e32 v126, 16, v123
	v_fmac_f32_e32 v122, v124, v124
	v_and_b32_e32 v123, 0xffff0000, v123
	v_fmac_f32_e32 v122, v126, v126
	v_fmac_f32_e32 v122, v123, v123
	global_store_dwordx2 v[136:137], v[118:119], off offset:256
	v_lshlrev_b32_e32 v123, 16, v118
	v_and_b32_e32 v118, 0xffff0000, v118
	v_mul_f32_e32 v118, v118, v118
	v_and_b32_e32 v127, 0xffff0000, v127
	v_lshlrev_b32_e32 v124, 16, v119
	v_fmac_f32_e32 v118, v123, v123
	v_fmac_f32_e32 v125, v127, v127
	v_and_b32_e32 v119, 0xffff0000, v119
	v_fmac_f32_e32 v118, v124, v124
	v_add_f32_e32 v122, v125, v122
	v_fmac_f32_e32 v118, v119, v119
	v_add_f32_e32 v118, v122, v118
	s_waitcnt vmcnt(0)
	v_lshlrev_b32_e32 v119, 16, v120
	v_and_b32_e32 v120, 0xffff0000, v120
	v_lshlrev_b32_e32 v122, 16, v121
	v_and_b32_e32 v121, 0xffff0000, v121
	v_add_f32_e32 v114, v114, v119
	v_add_f32_e32 v115, v115, v120
	v_add_f32_e32 v117, v117, v121
	v_add_f32_e32 v116, v116, v122
	v_cvt_pk_bf16_f32 v114, v114, v115
	v_cvt_pk_bf16_f32 v115, v116, v117
	global_store_dwordx2 v[136:137], v[114:115], off offset:288
	v_and_b32_e32 v117, 0xffff0000, v114
	v_lshlrev_b32_e32 v116, 16, v114
	v_mul_f32_e32 v117, v117, v117
	v_lshlrev_b32_e32 v119, 16, v115
	v_fmac_f32_e32 v117, v116, v116
	v_and_b32_e32 v120, 0xffff0000, v115
	v_fmac_f32_e32 v117, v119, v119
	v_fmac_f32_e32 v117, v120, v120
	v_add_f32_e32 v116, v118, v117
	ds_bpermute_b32 v117, v145, v116
	v_lshl_add_u64 v[114:115], v[140:141], 3, s[76:77]
	s_waitcnt lgkmcnt(0)
	v_add_f32_e32 v116, v116, v117
	ds_bpermute_b32 v117, v146, v116
	s_and_saveexec_b64 s[0:1], s[40:41]
	v_readlane_b32 s94, v254, 32
	s_movk_i32 s93, 0x1000
	v_readlane_b32 s95, v254, 33
	s_cbranch_execz .LBB0_262
	s_waitcnt lgkmcnt(0)
	v_add_f32_e32 v116, v116, v117
	s_mov_b32 s46, 0x49800000
	v_fma_f32 v116, v116, s46, 0.5
	v_trunc_f32_e32 v116, v116
	v_mul_f32_e32 v117, 0x2f800000, v116
	v_floor_f32_e32 v117, v117
	v_fmac_f32_e32 v116, 0xcf800000, v117
	v_cvt_u32_f32_e32 v116, v116
	v_cvt_u32_f32_e32 v117, v117
	global_atomic_add_x2 v[114:115], v[116:117], off

; template <class Epi>
; __device__ __forceinline__ void gemm_phase(LAS unsigned char* lds, const Gemm g, const StaticOrder& S, const Epi& E) {
;     ...
;         const bool has_next = S.next(ui + 1, nxt);
;         const char* nA = has_next ? (const char*)g.A + (size_t)nxt.pm * tstep : cA; const char* nB = has_next ? (const char*)g.Bt + (size_t)nxt.pn * tstep : cB;
;         for (int t = 0; t < nt; t += 2) {
;             const bool last = (t == nt - 2);
;             const char* a1 = cA + (size_t)(t + 1) * kstep;
;             const char* a2 = last ? nA : cA + (size_t)(t + 2) * kstep; const char* b2 = last ? nB : cB + (size_t)(t + 2) * kstep;
;             const char* a3 = a2 + kstep; const char* b3 = b2 + kstep;
;     ...
; #pragma unroll
;         for (int a = 0; a < 2; ++a)
; #pragma unroll
;             for (int b = 0; b < 2; ++b)
; #pragma unroll
;                 for (int m = 0; m < 4; ++m)
; #pragma unroll
;                     for (int n = 0; n < 2; ++n) acc[a][b][m][n] = (f32x4){0.f, 0.f, 0.f, 0.f};
;         cur = nxt; cA = nA; cB = nB; ++ui;
.LBB0_504:
	v_mov_b64_e32 v[2:3], 0x400
	s_ashr_i32 s39, s38, 31
	v_cmp_lt_i64_e32 vcc, s[42:43], v[2:3]
	s_lshl_b64 s[42:43], s[38:39], 19
	v_readlane_b32 s44, v252, 51
	v_readlane_b32 s45, v252, 52
	s_add_u32 s42, s44, s42
	s_addc_u32 s43, s45, s43
	s_and_b64 s[44:45], vcc, exec
	s_cselect_b32 s39, s43, s47
	s_cselect_b32 s58, s42, s46
	s_ashr_i32 s1, s0, 31
	s_lshl_b64 s[44:45], s[0:1], 19
	s_add_u32 s44, s22, s44
	s_addc_u32 s45, s23, s45
	s_and_b64 s[50:51], vcc, exec
	s_cselect_b32 s1, s45, s49
	s_cselect_b32 s59, s44, s48
	s_add_u32 s46, s46, 0x40080
	s_addc_u32 s47, s47, 0
	s_add_u32 s60, s48, 0x100
	v_mov_b32_e32 v2, 0
	s_addc_u32 s61, s49, 0
	s_mov_b32 s62, -2
	v_mov_b32_e32 v3, v2
	v_mov_b32_e32 v4, v2
	v_mov_b32_e32 v5, v2
	v_mov_b32_e32 v6, v2
	v_mov_b32_e32 v7, v2
	v_mov_b32_e32 v8, v2
	v_mov_b32_e32 v9, v2
	v_mov_b32_e32 v18, v2
	v_mov_b32_e32 v19, v2
	v_mov_b32_e32 v20, v2
	v_mov_b32_e32 v21, v2
	v_mov_b32_e32 v22, v2
	s_waitcnt lgkmcnt(0)
	v_mov_b32_e32 v23, v2
	v_mov_b32_e32 v24, v2
	v_mov_b32_e32 v25, v2
	v_mov_b32_e32 v34, v2
	v_mov_b32_e32 v35, v2
	v_mov_b32_e32 v36, v2
	v_mov_b32_e32 v37, v2
	v_mov_b32_e32 v38, v2
	v_mov_b32_e32 v39, v2
	v_mov_b32_e32 v40, v2
	v_mov_b32_e32 v41, v2
	v_mov_b32_e32 v50, v2
	v_mov_b32_e32 v51, v2
	v_mov_b32_e32 v52, v2
	v_mov_b32_e32 v53, v2
	v_mov_b32_e32 v54, v2
	v_mov_b32_e32 v55, v2
	v_mov_b32_e32 v56, v2
	v_mov_b32_e32 v57, v2
	v_mov_b32_e32 v10, v2
	v_mov_b32_e32 v11, v2
	v_mov_b32_e32 v12, v2
	v_mov_b32_e32 v13, v2
	v_mov_b32_e32 v14, v2
	v_mov_b32_e32 v15, v2
	v_mov_b32_e32 v16, v2
	v_mov_b32_e32 v17, v2
	v_mov_b32_e32 v26, v2
	v_mov_b32_e32 v27, v2
	v_mov_b32_e32 v28, v2
	v_mov_b32_e32 v29, v2
	v_mov_b32_e32 v30, v2
	v_mov_b32_e32 v31, v2
	v_mov_b32_e32 v32, v2
	v_mov_b32_e32 v33, v2
	v_mov_b32_e32 v42, v2
	v_mov_b32_e32 v43, v2
	v_mov_b32_e32 v44, v2
	v_mov_b32_e32 v45, v2
	v_mov_b32_e32 v46, v2
	v_mov_b32_e32 v47, v2
	v_mov_b32_e32 v48, v2
	v_mov_b32_e32 v49, v2
	v_mov_b32_e32 v58, v2
	v_mov_b32_e32 v59, v2
	v_mov_b32_e32 v60, v2
	v_mov_b32_e32 v61, v2
	v_mov_b32_e32 v62, v2
	v_mov_b32_e32 v63, v2
	v_mov_b32_e32 v64, v2
	v_mov_b32_e32 v65, v2
	v_mov_b32_e32 v66, v2
	v_mov_b32_e32 v67, v2
	v_mov_b32_e32 v68, v2
	v_mov_b32_e32 v69, v2
	v_mov_b32_e32 v70, v2
	v_mov_b32_e32 v71, v2
	v_mov_b32_e32 v72, v2
	v_mov_b32_e32 v73, v2
	v_mov_b32_e32 v82, v2
	v_mov_b32_e32 v83, v2
	v_mov_b32_e32 v84, v2
	v_mov_b32_e32 v85, v2
	v_mov_b32_e32 v86, v2
	v_mov_b32_e32 v87, v2
	v_mov_b32_e32 v88, v2
	v_mov_b32_e32 v89, v2
	v_mov_b32_e32 v98, v2
	v_mov_b32_e32 v99, v2
	v_mov_b32_e32 v100, v2
	v_mov_b32_e32 v101, v2
	v_mov_b32_e32 v102, v2
	v_mov_b32_e32 v103, v2
	v_mov_b32_e32 v104, v2
	v_mov_b32_e32 v105, v2
	v_mov_b32_e32 v114, v2
	v_mov_b32_e32 v115, v2
	v_mov_b32_e32 v116, v2
	v_mov_b32_e32 v117, v2
	v_mov_b32_e32 v118, v2
	v_mov_b32_e32 v119, v2
	v_mov_b32_e32 v120, v2
	v_mov_b32_e32 v121, v2
	v_mov_b32_e32 v74, v2
	v_mov_b32_e32 v75, v2
	v_mov_b32_e32 v76, v2
	v_mov_b32_e32 v77, v2
	v_mov_b32_e32 v78, v2
	v_mov_b32_e32 v79, v2
	v_mov_b32_e32 v80, v2
	v_mov_b32_e32 v81, v2
	v_mov_b32_e32 v90, v2
	v_mov_b32_e32 v91, v2
	v_mov_b32_e32 v92, v2
	v_mov_b32_e32 v93, v2
	v_mov_b32_e32 v94, v2
	v_mov_b32_e32 v95, v2
	v_mov_b32_e32 v96, v2
	v_mov_b32_e32 v97, v2
	v_mov_b32_e32 v106, v2
	v_mov_b32_e32 v107, v2
	v_mov_b32_e32 v108, v2
	v_mov_b32_e32 v109, v2
	v_mov_b32_e32 v110, v2
	v_mov_b32_e32 v111, v2
	v_mov_b32_e32 v112, v2
	v_mov_b32_e32 v113, v2
	v_mov_b32_e32 v122, v2
	v_mov_b32_e32 v123, v2
	v_mov_b32_e32 v124, v2
	v_mov_b32_e32 v125, v2
	v_mov_b32_e32 v126, v2
	v_mov_b32_e32 v127, v2
	v_mov_b32_e32 v128, v2
	v_mov_b32_e32 v129, v2
	s_cmpk_gt_u32 s2, 0xff
	s_cbranch_scc0 .Lprio_505
	s_setprio 1
; #define PG8_STAGE(bufoff, gbase, voff) do { _Pragma("unroll") for (int _i = 0; _i < 2; ++_i) \
;         __builtin_amdgcn_global_load_lds((const unsigned*)((const char*)(gbase) + (voff)[_i]), (LAS unsigned*)(lds + (bufoff) + ldsw + _i * 8192), 16, 0, 0); } while (0)
; #define PG8_LDA(dst, b, h) do { _Pragma("unroll") for (int m = 0; m < 4; ++m) _Pragma("unroll") for (int k = 0; k < 2; ++k) dst[m][k] = *(const LAS bf16x8*)(lds + PG8_SA(b, h) + aoff + m * 2048 + k * 1024); } while (0)
; #define PG8_LDB(dst, b, h) do { _Pragma("unroll") for (int n = 0; n < 2; ++n) _Pragma("unroll") for (int k = 0; k < 2; ++k) dst[n][k] = *(const LAS bf16x8*)(lds + PG8_SB(b, h) + boff + n * 2048 + k * 1024); } while (0)
; #define PG8_MMA(ai, bj, At, Bt) do { __builtin_amdgcn_s_setprio(1); _Pragma("unroll") for (int m = 0; m < 4; ++m) _Pragma("unroll") for (int n = 0; n < 2; ++n) _Pragma("unroll") for (int k = 0; k < 2; ++k) \
;         acc[ai][bj][m][n] = __builtin_amdgcn_mfma_f32_16x16x32_bf16(Bt[n][k], At[m][k], acc[ai][bj][m][n], 0, 0, 0); __builtin_amdgcn_s_setprio(0); } while (0)
; #define PG8_WAIT_V(n) asm volatile("s_waitcnt vmcnt(" #n ")" ::: "memory")
; #define PG8_WAIT_L(n) asm volatile("s_waitcnt lgkmcnt(" #n ")" ::: "memory")
; template <class Epi>
; __device__ __forceinline__ void gemm_phase(LAS unsigned char* lds, const Gemm g, const StaticOrder& S, const Epi& E) {
;     ...
;         for (int t = 0; t < nt; t += 2) {
;             const bool last = (t == nt - 2);
;             const char* a1 = cA + (size_t)(t + 1) * kstep;
;             const char* a2 = last ? nA : cA + (size_t)(t + 2) * kstep; const char* b2 = last ? nB : cB + (size_t)(t + 2) * kstep;
;             const char* a3 = a2 + kstep; const char* b3 = b2 + kstep;
;             PG8_LDB(B0, 0, 0); PG8_SCHED; PG8_LDA(At, 0, 0); PG8_STAGE(PG8_SA(1, 1), a1 + hstep, voffA);
;             PG8_WAIT_L(8); PG8_BAR; PG8_WAIT_L(0); PG8_MMA(0, 0, At, B0); PG8_BAR; PG8_SCHED;
;             PG8_LDB(B1, 0, 1); PG8_STAGE(PG8_SB(0, 0), b2, voffB);
;             PG8_BAR; PG8_WAIT_L(0); PG8_MMA(0, 1, At, B1); PG8_BAR;
;             PG8_LDA(At, 0, 1); PG8_STAGE(PG8_SA(0, 0), a2, voffA);
;             PG8_BAR; PG8_WAIT_L(0); PG8_MMA(1, 0, At, B0); PG8_BAR; PG8_SCHED;
;             PG8_STAGE(PG8_SB(0, 1), b2 + hstep, voffB);
;             PG8_WAIT_V(6); PG8_BAR; PG8_MMA(1, 1, At, B1); PG8_BAR;
.Lprio_505:
.LBB0_505:
	s_add_u32 s48, s46, 0xfffc0080
	s_addc_u32 s49, s47, -1
	s_add_i32 s63, 0, 0x10000
	v_add_u32_e32 v152, s63, v171
	ds_read_b128 v[140:143], v152
	ds_read_b128 v[144:147], v152 offset:1024
	ds_read_b128 v[148:151], v152 offset:2048
	ds_read_b128 v[152:155], v152 offset:3072
	s_cmp_eq_u32 s62, 12
	s_cselect_b32 s51, s39, s49
	s_cselect_b32 s50, s58, s48
	s_cselect_b32 s49, s1, s61
	s_cselect_b32 s48, s59, s60
	v_lshl_add_u64 v[160:161], s[46:47], 0, v[136:137]
	s_add_i32 m0, s24, 0xc000
	ds_read_b128 v[156:159], v179
	ds_read_b128 v[180:183], v179 offset:1024
	ds_read_b128 v[184:187], v179 offset:2048
	ds_read_b128 v[188:191], v179 offset:3072
	ds_read_b128 v[192:195], v179 offset:4096
	ds_read_b128 v[196:199], v179 offset:5120
	ds_read_b128 v[200:203], v179 offset:6144
	ds_read_b128 v[204:207], v179 offset:7168
	global_load_lds_dwordx4 v[160:161], off
	v_lshl_add_u64 v[160:161], s[46:47], 0, v[138:139]
	s_add_i32 m0, s24, 0xe000
	s_nop 0
	global_load_lds_dwordx4 v[160:161], off
	s_waitcnt lgkmcnt(8)
	s_barrier
	s_waitcnt lgkmcnt(0)
	s_waitcnt lgkmcnt(0)
	v_mfma_f32_16x16x32_bf16 v[126:129], v[140:143], v[156:159], v[126:129]
	v_mfma_f32_16x16x32_bf16 v[122:125], v[148:151], v[156:159], v[122:125]
	v_mfma_f32_16x16x32_bf16 v[110:113], v[140:143], v[184:187], v[110:113]
	v_mfma_f32_16x16x32_bf16 v[106:109], v[148:151], v[184:187], v[106:109]
	v_mfma_f32_16x16x32_bf16 v[94:97], v[140:143], v[192:195], v[94:97]
	v_mfma_f32_16x16x32_bf16 v[90:93], v[148:151], v[192:195], v[90:93]
	v_mfma_f32_16x16x32_bf16 v[78:81], v[140:143], v[200:203], v[78:81]
	v_mfma_f32_16x16x32_bf16 v[74:77], v[148:151], v[200:203], v[74:77]
	v_mfma_f32_16x16x32_bf16 v[126:129], v[144:147], v[180:183], v[126:129]
	v_mfma_f32_16x16x32_bf16 v[122:125], v[152:155], v[180:183], v[122:125]
	v_mfma_f32_16x16x32_bf16 v[110:113], v[144:147], v[188:191], v[110:113]
	v_mfma_f32_16x16x32_bf16 v[106:109], v[152:155], v[188:191], v[106:109]
	v_mfma_f32_16x16x32_bf16 v[94:97], v[144:147], v[196:199], v[94:97]
	v_mfma_f32_16x16x32_bf16 v[90:93], v[152:155], v[196:199], v[90:93]
	v_mfma_f32_16x16x32_bf16 v[78:81], v[144:147], v[204:207], v[78:81]
	v_mfma_f32_16x16x32_bf16 v[74:77], v[152:155], v[204:207], v[74:77]
	s_barrier
	s_add_i32 s66, 0, 0x14000
	v_add_u32_e32 v160, s66, v171
	s_add_i32 s63, s63, s3
	ds_read_b128 v[208:211], v160
	ds_read_b128 v[212:215], v160 offset:1024
	ds_read_b128 v[216:219], v160 offset:2048
	ds_read_b128 v[220:223], v160 offset:3072
	v_lshl_add_u64 v[160:161], s[48:49], 0, v[0:1]
	s_mov_b32 m0, s63
	v_lshl_add_u64 v[172:173], s[48:49], 0, v[130:131]
	global_load_lds_dwordx4 v[160:161], off
	s_add_i32 m0, s63, 0x2000
	s_nop 0
	global_load_lds_dwordx4 v[172:173], off
	s_barrier
	s_waitcnt lgkmcnt(0)
	s_waitcnt lgkmcnt(0)
	v_mfma_f32_16x16x32_bf16 v[118:121], v[208:211], v[156:159], v[118:121]
	v_mfma_f32_16x16x32_bf16 v[114:117], v[216:219], v[156:159], v[114:117]
	v_mfma_f32_16x16x32_bf16 v[102:105], v[208:211], v[184:187], v[102:105]
	v_mfma_f32_16x16x32_bf16 v[98:101], v[216:219], v[184:187], v[98:101]
	v_mfma_f32_16x16x32_bf16 v[86:89], v[208:211], v[192:195], v[86:89]
	v_mfma_f32_16x16x32_bf16 v[82:85], v[216:219], v[192:195], v[82:85]
	v_mfma_f32_16x16x32_bf16 v[70:73], v[208:211], v[200:203], v[70:73]
	v_mfma_f32_16x16x32_bf16 v[66:69], v[216:219], v[200:203], v[66:69]
	v_mfma_f32_16x16x32_bf16 v[118:121], v[212:215], v[180:183], v[118:121]
	v_mfma_f32_16x16x32_bf16 v[114:117], v[220:223], v[180:183], v[114:117]
	v_mfma_f32_16x16x32_bf16 v[102:105], v[212:215], v[188:191], v[102:105]
	v_mfma_f32_16x16x32_bf16 v[98:101], v[220:223], v[188:191], v[98:101]
	v_mfma_f32_16x16x32_bf16 v[86:89], v[212:215], v[196:199], v[86:89]
	v_mfma_f32_16x16x32_bf16 v[82:85], v[220:223], v[196:199], v[82:85]
	v_mfma_f32_16x16x32_bf16 v[70:73], v[212:215], v[204:207], v[70:73]
	v_mfma_f32_16x16x32_bf16 v[66:69], v[220:223], v[204:207], v[66:69]
	s_mov_b32 m0, s24
	v_lshl_add_u64 v[174:175], s[50:51], 0, v[134:135]
	s_barrier
	ds_read_b128 v[156:159], v179 offset:16384
	ds_read_b128 v[180:183], v179 offset:17408
	ds_read_b128 v[184:187], v179 offset:18432
	ds_read_b128 v[188:191], v179 offset:19456
	ds_read_b128 v[192:195], v179 offset:20480
	ds_read_b128 v[196:199], v179 offset:21504
	ds_read_b128 v[200:203], v179 offset:22528
	ds_read_b128 v[204:207], v179 offset:23552
	global_load_lds_dwordx4 v[174:175], off
	v_lshl_add_u64 v[176:177], s[50:51], 0, v[132:133]
	s_mov_b32 m0, s26
	s_nop 0
	global_load_lds_dwordx4 v[176:177], off
	s_barrier
	s_waitcnt lgkmcnt(0)
	s_waitcnt lgkmcnt(0)
	v_mfma_f32_16x16x32_bf16 v[62:65], v[140:143], v[156:159], v[62:65]
	v_mfma_f32_16x16x32_bf16 v[58:61], v[148:151], v[156:159], v[58:61]
	v_mfma_f32_16x16x32_bf16 v[46:49], v[140:143], v[184:187], v[46:49]
	v_mfma_f32_16x16x32_bf16 v[42:45], v[148:151], v[184:187], v[42:45]
	v_mfma_f32_16x16x32_bf16 v[30:33], v[140:143], v[192:195], v[30:33]
	v_mfma_f32_16x16x32_bf16 v[26:29], v[148:151], v[192:195], v[26:29]
	v_mfma_f32_16x16x32_bf16 v[14:17], v[140:143], v[200:203], v[14:17]
	v_mfma_f32_16x16x32_bf16 v[10:13], v[148:151], v[200:203], v[10:13]
	v_mfma_f32_16x16x32_bf16 v[62:65], v[144:147], v[180:183], v[62:65]
	v_mfma_f32_16x16x32_bf16 v[58:61], v[152:155], v[180:183], v[58:61]
	v_mfma_f32_16x16x32_bf16 v[46:49], v[144:147], v[188:191], v[46:49]
	v_mfma_f32_16x16x32_bf16 v[42:45], v[152:155], v[188:191], v[42:45]
	v_mfma_f32_16x16x32_bf16 v[30:33], v[144:147], v[196:199], v[30:33]
	v_mfma_f32_16x16x32_bf16 v[26:29], v[152:155], v[196:199], v[26:29]
	v_mfma_f32_16x16x32_bf16 v[14:17], v[144:147], v[204:207], v[14:17]
	v_mfma_f32_16x16x32_bf16 v[10:13], v[152:155], v[204:207], v[10:13]
	s_barrier
	s_add_u32 s64, s48, 0x40000
	s_addc_u32 s65, s49, 0
	s_add_i32 s63, s66, s3
	v_lshl_add_u64 v[140:141], s[64:65], 0, v[0:1]
	s_mov_b32 m0, s63
	s_nop 0
	global_load_lds_dwordx4 v[140:141], off
	v_lshl_add_u64 v[140:141], s[64:65], 0, v[130:131]
	s_add_i32 m0, s63, 0x2000
	s_nop 0
	global_load_lds_dwordx4 v[140:141], off
	s_cmp_lg_u32 s62, -2
	s_cbranch_scc1 .Lrx_s0_std
	s_cmp_lt_u32 s55, 2
	s_cbranch_scc1 .Lrx_s0_std
	s_waitcnt vmcnt(24)
	s_branch .Lrx_s0_done

; #define PG8_STAGE(bufoff, gbase, voff) do { _Pragma("unroll") for (int _i = 0; _i < 2; ++_i) \
;         __builtin_amdgcn_global_load_lds((const unsigned*)((const char*)(gbase) + (voff)[_i]), (LAS unsigned*)(lds + (bufoff) + ldsw + _i * 8192), 16, 0, 0); } while (0)
; #define PG8_LDA(dst, b, h) do { _Pragma("unroll") for (int m = 0; m < 4; ++m) _Pragma("unroll") for (int k = 0; k < 2; ++k) dst[m][k] = *(const LAS bf16x8*)(lds + PG8_SA(b, h) + aoff + m * 2048 + k * 1024); } while (0)
; #define PG8_LDB(dst, b, h) do { _Pragma("unroll") for (int n = 0; n < 2; ++n) _Pragma("unroll") for (int k = 0; k < 2; ++k) dst[n][k] = *(const LAS bf16x8*)(lds + PG8_SB(b, h) + boff + n * 2048 + k * 1024); } while (0)
; #define PG8_MMA(ai, bj, At, Bt) do { __builtin_amdgcn_s_setprio(1); _Pragma("unroll") for (int m = 0; m < 4; ++m) _Pragma("unroll") for (int n = 0; n < 2; ++n) _Pragma("unroll") for (int k = 0; k < 2; ++k) \
;         acc[ai][bj][m][n] = __builtin_amdgcn_mfma_f32_16x16x32_bf16(Bt[n][k], At[m][k], acc[ai][bj][m][n], 0, 0, 0); __builtin_amdgcn_s_setprio(0); } while (0)
; #define PG8_WAIT_V(n) asm volatile("s_waitcnt vmcnt(" #n ")" ::: "memory")
; #define PG8_WAIT_L(n) asm volatile("s_waitcnt lgkmcnt(" #n ")" ::: "memory")
; #define PG8_BAR __builtin_amdgcn_s_barrier()
; #define PG8_SCHED __builtin_amdgcn_sched_barrier(0)
; template <class Epi>
; __device__ __forceinline__ void gemm_phase(LAS unsigned char* lds, const Gemm g, const StaticOrder& S, const Epi& E) {
;     ...
;             PG8_BAR; PG8_WAIT_L(0); PG8_MMA(1, 0, At, B0); PG8_BAR; PG8_SCHED;
;             PG8_STAGE(PG8_SB(0, 1), b2 + hstep, voffB);
;             PG8_WAIT_V(6); PG8_BAR; PG8_MMA(1, 1, At, B1); PG8_BAR;
;             PG8_LDB(B0, 1, 0); PG8_SCHED; PG8_LDA(At, 1, 0); PG8_STAGE(PG8_SA(0, 1), a2 + hstep, voffA);
;             PG8_WAIT_L(8); PG8_BAR; PG8_WAIT_L(0); PG8_MMA(0, 0, At, B0); PG8_BAR; PG8_SCHED;
;             PG8_LDB(B1, 1, 1); PG8_STAGE(PG8_SB(1, 0), b3, voffB);
;             PG8_BAR; PG8_WAIT_L(0); PG8_MMA(0, 1, At, B1); PG8_BAR;
;             PG8_LDA(At, 1, 1); PG8_STAGE(PG8_SA(1, 0), a3, voffA);
;             PG8_BAR; PG8_WAIT_L(0); PG8_MMA(1, 0, At, B0); PG8_BAR; PG8_SCHED;
;             PG8_STAGE(PG8_SB(1, 1), b3 + hstep, voffB);
;             PG8_WAIT_V(6); PG8_BAR; PG8_MMA(1, 1, At, B1); PG8_BAR;
.Lrx_s0_done:
	s_barrier
	v_mfma_f32_16x16x32_bf16 v[54:57], v[208:211], v[156:159], v[54:57]
	v_mfma_f32_16x16x32_bf16 v[50:53], v[216:219], v[156:159], v[50:53]
	v_mfma_f32_16x16x32_bf16 v[38:41], v[208:211], v[184:187], v[38:41]
	v_mfma_f32_16x16x32_bf16 v[34:37], v[216:219], v[184:187], v[34:37]
	v_mfma_f32_16x16x32_bf16 v[22:25], v[208:211], v[192:195], v[22:25]
	v_mfma_f32_16x16x32_bf16 v[18:21], v[216:219], v[192:195], v[18:21]
	v_mfma_f32_16x16x32_bf16 v[6:9], v[208:211], v[200:203], v[6:9]
	v_mfma_f32_16x16x32_bf16 v[2:5], v[216:219], v[200:203], v[2:5]
	v_mfma_f32_16x16x32_bf16 v[54:57], v[212:215], v[180:183], v[54:57]
	v_mfma_f32_16x16x32_bf16 v[50:53], v[220:223], v[180:183], v[50:53]
	v_mfma_f32_16x16x32_bf16 v[38:41], v[212:215], v[188:191], v[38:41]
	v_mfma_f32_16x16x32_bf16 v[34:37], v[220:223], v[188:191], v[34:37]
	v_mfma_f32_16x16x32_bf16 v[22:25], v[212:215], v[196:199], v[22:25]
	v_mfma_f32_16x16x32_bf16 v[18:21], v[220:223], v[196:199], v[18:21]
	v_mfma_f32_16x16x32_bf16 v[6:9], v[212:215], v[204:207], v[6:9]
	v_mfma_f32_16x16x32_bf16 v[2:5], v[220:223], v[204:207], v[2:5]
	s_add_i32 s63, 0, 0x18000
	v_add_u32_e32 v152, s63, v171
	s_barrier
	ds_read_b128 v[140:143], v152
	ds_read_b128 v[144:147], v152 offset:1024
	ds_read_b128 v[148:151], v152 offset:2048
	ds_read_b128 v[152:155], v152 offset:3072
	s_add_u32 s50, s50, 0x40000
	s_addc_u32 s51, s51, 0
	s_mov_b32 m0, s30
	v_lshl_add_u64 v[208:209], s[50:51], 0, v[134:135]
	ds_read_b128 v[156:159], v179 offset:32768
	ds_read_b128 v[180:183], v179 offset:33792
	ds_read_b128 v[184:187], v179 offset:34816
	ds_read_b128 v[188:191], v179 offset:35840
	ds_read_b128 v[192:195], v179 offset:36864
	ds_read_b128 v[196:199], v179 offset:37888
	ds_read_b128 v[200:203], v179 offset:38912
	ds_read_b128 v[204:207], v179 offset:39936
	global_load_lds_dwordx4 v[208:209], off
	v_lshl_add_u64 v[208:209], s[50:51], 0, v[132:133]
	s_mov_b32 m0, s52
	s_nop 0
	global_load_lds_dwordx4 v[208:209], off
	s_waitcnt lgkmcnt(8)
	s_barrier
	s_waitcnt lgkmcnt(0)
	s_waitcnt lgkmcnt(0)
	v_mfma_f32_16x16x32_bf16 v[126:129], v[140:143], v[156:159], v[126:129]
	v_mfma_f32_16x16x32_bf16 v[122:125], v[148:151], v[156:159], v[122:125]
	v_mfma_f32_16x16x32_bf16 v[110:113], v[140:143], v[184:187], v[110:113]
	v_mfma_f32_16x16x32_bf16 v[106:109], v[148:151], v[184:187], v[106:109]
	v_mfma_f32_16x16x32_bf16 v[94:97], v[140:143], v[192:195], v[94:97]
	v_mfma_f32_16x16x32_bf16 v[90:93], v[148:151], v[192:195], v[90:93]
	v_mfma_f32_16x16x32_bf16 v[78:81], v[140:143], v[200:203], v[78:81]
	v_mfma_f32_16x16x32_bf16 v[74:77], v[148:151], v[200:203], v[74:77]
	v_mfma_f32_16x16x32_bf16 v[126:129], v[144:147], v[180:183], v[126:129]
	v_mfma_f32_16x16x32_bf16 v[122:125], v[152:155], v[180:183], v[122:125]
	v_mfma_f32_16x16x32_bf16 v[110:113], v[144:147], v[188:191], v[110:113]
	v_mfma_f32_16x16x32_bf16 v[106:109], v[152:155], v[188:191], v[106:109]
	v_mfma_f32_16x16x32_bf16 v[94:97], v[144:147], v[196:199], v[94:97]
	v_mfma_f32_16x16x32_bf16 v[90:93], v[152:155], v[196:199], v[90:93]
	v_mfma_f32_16x16x32_bf16 v[78:81], v[144:147], v[204:207], v[78:81]
	v_mfma_f32_16x16x32_bf16 v[74:77], v[152:155], v[204:207], v[74:77]
	s_barrier
	s_add_i32 s50, 0, 0x1c000
	s_add_i32 s51, s63, s3
	v_add_u32_e32 v220, s50, v171
	v_lshl_add_u64 v[160:161], v[160:161], 0, s[28:29]
	s_mov_b32 m0, s51
	ds_read_b128 v[208:211], v220
	ds_read_b128 v[212:215], v220 offset:1024
	ds_read_b128 v[216:219], v220 offset:2048
	ds_read_b128 v[220:223], v220 offset:3072
	global_load_lds_dwordx4 v[160:161], off
	v_lshl_add_u64 v[160:161], v[172:173], 0, s[28:29]
	s_add_i32 m0, s51, 0x2000
	s_nop 0
	global_load_lds_dwordx4 v[160:161], off
	s_barrier
	s_waitcnt lgkmcnt(0)
	s_waitcnt lgkmcnt(0)
	v_mfma_f32_16x16x32_bf16 v[118:121], v[208:211], v[156:159], v[118:121]
	v_mfma_f32_16x16x32_bf16 v[114:117], v[216:219], v[156:159], v[114:117]
	v_mfma_f32_16x16x32_bf16 v[102:105], v[208:211], v[184:187], v[102:105]
	v_mfma_f32_16x16x32_bf16 v[98:101], v[216:219], v[184:187], v[98:101]
	v_mfma_f32_16x16x32_bf16 v[86:89], v[208:211], v[192:195], v[86:89]
	v_mfma_f32_16x16x32_bf16 v[82:85], v[216:219], v[192:195], v[82:85]
	v_mfma_f32_16x16x32_bf16 v[70:73], v[208:211], v[200:203], v[70:73]
	v_mfma_f32_16x16x32_bf16 v[66:69], v[216:219], v[200:203], v[66:69]
	v_mfma_f32_16x16x32_bf16 v[118:121], v[212:215], v[180:183], v[118:121]
	v_mfma_f32_16x16x32_bf16 v[114:117], v[220:223], v[180:183], v[114:117]
	v_mfma_f32_16x16x32_bf16 v[102:105], v[212:215], v[188:191], v[102:105]
	v_mfma_f32_16x16x32_bf16 v[98:101], v[220:223], v[188:191], v[98:101]
	v_mfma_f32_16x16x32_bf16 v[86:89], v[212:215], v[196:199], v[86:89]
	v_mfma_f32_16x16x32_bf16 v[82:85], v[220:223], v[196:199], v[82:85]
	v_mfma_f32_16x16x32_bf16 v[70:73], v[212:215], v[204:207], v[70:73]
	v_mfma_f32_16x16x32_bf16 v[66:69], v[220:223], v[204:207], v[66:69]
	s_mov_b32 m0, s53
	v_lshl_add_u64 v[160:161], v[174:175], 0, s[28:29]
	s_waitcnt vmcnt(10)
	s_barrier
	ds_read_b128 v[156:159], v179 offset:49152
	ds_read_b128 v[180:183], v179 offset:50176
	ds_read_b128 v[184:187], v179 offset:51200
	ds_read_b128 v[188:191], v179 offset:52224
	ds_read_b128 v[192:195], v179 offset:53248
	ds_read_b128 v[196:199], v179 offset:54272
	ds_read_b128 v[200:203], v179 offset:55296
	ds_read_b128 v[204:207], v179 offset:56320
	global_load_lds_dwordx4 v[160:161], off
	v_lshl_add_u64 v[160:161], v[176:177], 0, s[28:29]
	s_mov_b32 m0, s54
	s_nop 0
	global_load_lds_dwordx4 v[160:161], off
	s_barrier
; __device__ __forceinline__ float rstd_fix(u64 v) { return rsqrtf((float)v * (1.f / (1048576.f * 1024.f)) + 1e-6f); }
; __device__ __forceinline__ unsigned pk2(float lo, float hi) { unsigned r; asm volatile("v_cvt_pk_bf16_f32 %0, %1, %2" : "=v"(r) : "v"(lo), "v"(hi)); return r; }
; #define PG8_STAGE(bufoff, gbase, voff) do { _Pragma("unroll") for (int _i = 0; _i < 2; ++_i) \
;         __builtin_amdgcn_global_load_lds((const unsigned*)((const char*)(gbase) + (voff)[_i]), (LAS unsigned*)(lds + (bufoff) + ldsw + _i * 8192), 16, 0, 0); } while (0)
; #define PG8_MMA(ai, bj, At, Bt) do { __builtin_amdgcn_s_setprio(1); _Pragma("unroll") for (int m = 0; m < 4; ++m) _Pragma("unroll") for (int n = 0; n < 2; ++n) _Pragma("unroll") for (int k = 0; k < 2; ++k) \
;         acc[ai][bj][m][n] = __builtin_amdgcn_mfma_f32_16x16x32_bf16(Bt[n][k], At[m][k], acc[ai][bj][m][n], 0, 0, 0); __builtin_amdgcn_s_setprio(0); } while (0)
; #define PG8_WAIT_V(n) asm volatile("s_waitcnt vmcnt(" #n ")" ::: "memory")
; template <class Epi>
; __device__ __forceinline__ void gemm_phase(LAS unsigned char* lds, const Gemm g, const StaticOrder& S, const Epi& E) {
;     ...
;             PG8_BAR; PG8_WAIT_L(0); PG8_MMA(1, 0, At, B0); PG8_BAR; PG8_SCHED;
;             PG8_STAGE(PG8_SB(1, 1), b3 + hstep, voffB);
;             PG8_WAIT_V(6); PG8_BAR; PG8_MMA(1, 1, At, B1); PG8_BAR;
;     __device__ __forceinline__ void operator()(const f32x4 (&acc)[2][2][4][2], const Unit& u, int wr, int wc, int fr, int fq) const {
;         const int row0 = u.pm * BM + wr * 64 + fr, col0 = u.pn * BM + wc * 32 + 8 * fq;
;         u64 rv[2][4];
; #pragma unroll
;         for (int ai = 0; ai < 2; ++ai)
; #pragma unroll
;             for (int m = 0; m < 4; ++m) rv[ai][m] = rss[row0 + ai * HALF + m * 16];
; #pragma unroll
;         for (int ai = 0; ai < 2; ++ai)
; #pragma unroll
;             for (int m = 0; m < 4; ++m) { const int row = row0 + ai * HALF + m * 16; bf16_t* rowp = O + (size_t)row * ldc + col0;
;                 const float rs = rstd_fix(rv[ai][m]);
; #pragma unroll
;                 for (int bj = 0; bj < 2; ++bj) { const f32x4 v0 = acc[ai][bj][m][0] * rs, v1 = acc[ai][bj][m][1] * rs;
;                     u32x4 w; w.x = pk2(v0[0], v0[1]); w.y = pk2(v0[2], v0[3]); w.z = pk2(v1[0], v1[1]); w.w = pk2(v1[2], v1[3]);
;                     *(u32x4*)(rowp + bj * HALF) = w; } }
	s_waitcnt lgkmcnt(0)
	s_waitcnt lgkmcnt(0)
	v_mfma_f32_16x16x32_bf16 v[62:65], v[140:143], v[156:159], v[62:65]
	v_mfma_f32_16x16x32_bf16 v[58:61], v[148:151], v[156:159], v[58:61]
	v_mfma_f32_16x16x32_bf16 v[46:49], v[140:143], v[184:187], v[46:49]
	v_mfma_f32_16x16x32_bf16 v[42:45], v[148:151], v[184:187], v[42:45]
	v_mfma_f32_16x16x32_bf16 v[30:33], v[140:143], v[192:195], v[30:33]
	v_mfma_f32_16x16x32_bf16 v[26:29], v[148:151], v[192:195], v[26:29]
	v_mfma_f32_16x16x32_bf16 v[14:17], v[140:143], v[200:203], v[14:17]
	v_mfma_f32_16x16x32_bf16 v[10:13], v[148:151], v[200:203], v[10:13]
	v_mfma_f32_16x16x32_bf16 v[62:65], v[144:147], v[180:183], v[62:65]
	v_mfma_f32_16x16x32_bf16 v[58:61], v[152:155], v[180:183], v[58:61]
	v_mfma_f32_16x16x32_bf16 v[46:49], v[144:147], v[188:191], v[46:49]
	v_mfma_f32_16x16x32_bf16 v[42:45], v[152:155], v[188:191], v[42:45]
	v_mfma_f32_16x16x32_bf16 v[30:33], v[144:147], v[196:199], v[30:33]
	v_mfma_f32_16x16x32_bf16 v[26:29], v[152:155], v[196:199], v[26:29]
	v_mfma_f32_16x16x32_bf16 v[14:17], v[144:147], v[204:207], v[14:17]
	v_mfma_f32_16x16x32_bf16 v[10:13], v[152:155], v[204:207], v[10:13]
	s_barrier
	s_add_u32 s48, s48, 0x40080
	s_addc_u32 s49, s49, 0
	s_add_i32 s50, s50, s3
	v_lshl_add_u64 v[140:141], s[48:49], 0, v[0:1]
	s_mov_b32 m0, s50
	s_nop 0
	global_load_lds_dwordx4 v[140:141], off
	v_lshl_add_u64 v[140:141], s[48:49], 0, v[130:131]
	s_add_i32 m0, s50, 0x2000
	s_nop 0
	global_load_lds_dwordx4 v[140:141], off
	s_waitcnt vmcnt(6)
	s_barrier
	v_mfma_f32_16x16x32_bf16 v[54:57], v[208:211], v[156:159], v[54:57]
	v_mfma_f32_16x16x32_bf16 v[50:53], v[216:219], v[156:159], v[50:53]
	v_mfma_f32_16x16x32_bf16 v[38:41], v[208:211], v[184:187], v[38:41]
	v_mfma_f32_16x16x32_bf16 v[34:37], v[216:219], v[184:187], v[34:37]
	v_mfma_f32_16x16x32_bf16 v[22:25], v[208:211], v[192:195], v[22:25]
	v_mfma_f32_16x16x32_bf16 v[18:21], v[216:219], v[192:195], v[18:21]
	v_mfma_f32_16x16x32_bf16 v[6:9], v[208:211], v[200:203], v[6:9]
	v_mfma_f32_16x16x32_bf16 v[2:5], v[216:219], v[200:203], v[2:5]
	v_mfma_f32_16x16x32_bf16 v[54:57], v[212:215], v[180:183], v[54:57]
	v_mfma_f32_16x16x32_bf16 v[50:53], v[220:223], v[180:183], v[50:53]
	v_mfma_f32_16x16x32_bf16 v[38:41], v[212:215], v[188:191], v[38:41]
	v_mfma_f32_16x16x32_bf16 v[34:37], v[220:223], v[188:191], v[34:37]
	v_mfma_f32_16x16x32_bf16 v[22:25], v[212:215], v[196:199], v[22:25]
	v_mfma_f32_16x16x32_bf16 v[18:21], v[220:223], v[196:199], v[18:21]
	v_mfma_f32_16x16x32_bf16 v[6:9], v[212:215], v[204:207], v[6:9]
	v_mfma_f32_16x16x32_bf16 v[2:5], v[220:223], v[204:207], v[2:5]
	s_add_i32 s62, s62, 2
	s_add_u32 s46, s46, 0x100
	s_addc_u32 s47, s47, 0
	s_add_u32 s60, s60, 0x100
	s_addc_u32 s61, s61, 0
	s_cmp_gt_u32 s62, 13
	s_barrier
	s_cbranch_scc0 .LBB0_505
	s_setprio 0
	v_lshl_add_u32 v142, s57, 8, v168
	v_ashrrev_i32_e32 v143, 31, v142
	s_nop 0
	v_lshl_or_b32 v154, s56, 8, v178
	v_or_b32_e32 v160, 16, v142
	v_or_b32_e32 v158, 32, v142
	v_or_b32_e32 v152, 48, v142
	v_ashrrev_i32_e32 v155, 31, v154
	v_lshlrev_b64 v[142:143], 13, v[142:143]
	v_lshl_add_u64 v[142:143], s[34:35], 0, v[142:143]
	v_lshlrev_b64 v[154:155], 1, v[154:155]
	v_lshl_add_u64 v[142:143], v[142:143], 0, v[154:155]
	v_ashrrev_i32_e32 v161, 31, v160
	v_ashrrev_i32_e32 v159, 31, v158
	v_ashrrev_i32_e32 v153, 31, v152
	s_mov_b32 s1, 0x100000
	s_mov_b64 s[46:47], 0x100000
	s_mov_b32 s56, s0
	s_mov_b32 s57, s38
	s_mov_b64 s[48:49], s[44:45]
	v_mov_b32_e32 v172, v236
	s_nop 0
	s_nop 0
	v_pk_mul_f32 v[128:129], v[128:129], v[172:173] op_sel_hi:[1,0]
	v_pk_mul_f32 v[126:127], v[126:127], v[172:173] op_sel_hi:[1,0]
	v_pk_mul_f32 v[174:175], v[124:125], v[172:173] op_sel_hi:[1,0]
	v_pk_mul_f32 v[124:125], v[122:123], v[172:173] op_sel_hi:[1,0]
	v_cvt_pk_bf16_f32 v122, v126, v127
	v_cvt_pk_bf16_f32 v123, v128, v129
	v_pk_mul_f32 v[120:121], v[120:121], v[172:173] op_sel_hi:[1,0]
	v_cvt_pk_bf16_f32 v124, v124, v125
	v_cvt_pk_bf16_f32 v125, v174, v175
	global_store_dwordx4 v[142:143], v[122:125], off nt
	v_pk_mul_f32 v[118:119], v[118:119], v[172:173] op_sel_hi:[1,0]
	s_nop 0
	v_pk_mul_f32 v[122:123], v[116:117], v[172:173] op_sel_hi:[1,0]
	v_pk_mul_f32 v[116:117], v[114:115], v[172:173] op_sel_hi:[1,0]
	v_cvt_pk_bf16_f32 v114, v118, v119
	v_cvt_pk_bf16_f32 v115, v120, v121
	s_nop 0
	v_cvt_pk_bf16_f32 v116, v116, v117
	v_cvt_pk_bf16_f32 v117, v122, v123
	global_store_dwordx4 v[142:143], v[114:117], off offset:256 nt
	s_nop 1
	v_mov_b32_e32 v116, v237
	v_lshlrev_b64 v[114:115], 13, v[160:161]
	v_lshl_add_u64 v[114:115], s[34:35], 0, v[114:115]
	v_lshl_add_u64 v[114:115], v[114:115], 0, v[154:155]
	s_nop 0
	v_pk_mul_f32 v[112:113], v[112:113], v[116:117] op_sel_hi:[1,0]
	v_pk_mul_f32 v[110:111], v[110:111], v[116:117] op_sel_hi:[1,0]
	v_pk_mul_f32 v[118:119], v[108:109], v[116:117] op_sel_hi:[1,0]
	v_pk_mul_f32 v[108:109], v[106:107], v[116:117] op_sel_hi:[1,0]
	v_cvt_pk_bf16_f32 v106, v110, v111
	v_cvt_pk_bf16_f32 v107, v112, v113
	v_pk_mul_f32 v[104:105], v[104:105], v[116:117] op_sel_hi:[1,0]
	v_cvt_pk_bf16_f32 v108, v108, v109
	v_cvt_pk_bf16_f32 v109, v118, v119
	global_store_dwordx4 v[114:115], v[106:109], off nt
	v_pk_mul_f32 v[102:103], v[102:103], v[116:117] op_sel_hi:[1,0]
	s_nop 0
	v_pk_mul_f32 v[106:107], v[100:101], v[116:117] op_sel_hi:[1,0]
	v_pk_mul_f32 v[100:101], v[98:99], v[116:117] op_sel_hi:[1,0]
	v_cvt_pk_bf16_f32 v98, v102, v103
	v_cvt_pk_bf16_f32 v99, v104, v105
	s_nop 0
	v_cvt_pk_bf16_f32 v100, v100, v101
	v_cvt_pk_bf16_f32 v101, v106, v107
	global_store_dwordx4 v[114:115], v[98:101], off offset:256 nt
	s_nop 1
	v_mov_b32_e32 v100, v241
	v_lshlrev_b64 v[98:99], 13, v[158:159]
; __device__ __forceinline__ float rstd_fix(u64 v) { return rsqrtf((float)v * (1.f / (1048576.f * 1024.f)) + 1e-6f); }
; __device__ __forceinline__ unsigned pk2(float lo, float hi) { unsigned r; asm volatile("v_cvt_pk_bf16_f32 %0, %1, %2" : "=v"(r) : "v"(lo), "v"(hi)); return r; }
; #define PG8_WAIT_V(n) asm volatile("s_waitcnt vmcnt(" #n ")" ::: "memory")
; #define PG8_BAR __builtin_amdgcn_s_barrier()
; template <class Epi>
; __device__ __forceinline__ void gemm_phase(LAS unsigned char* lds, const Gemm g, const StaticOrder& S, const Epi& E) {
;     ...
;         if constexpr (Epi::AFTER_DRAIN) { if (has_next) E(acc, cur, wr, wc, fr, fq); } else E(acc, cur, wr, wc, fr, fq);
;         if (!has_next) break;
; #pragma unroll
;         for (int a = 0; a < 2; ++a)
; #pragma unroll
;             for (int b = 0; b < 2; ++b)
; #pragma unroll
;                 for (int m = 0; m < 4; ++m)
; #pragma unroll
;                     for (int n = 0; n < 2; ++n) acc[a][b][m][n] = (f32x4){0.f, 0.f, 0.f, 0.f};
;         cur = nxt; cA = nA; cB = nB; ++ui;
;     }
;     PG8_WAIT_V(0);
;     if (wr == 0) PG8_BAR;
;     PG8_BAR;
;     __device__ __forceinline__ void operator()(const f32x4 (&acc)[2][2][4][2], const Unit& u, int wr, int wc, int fr, int fq) const {
;     ...
;         for (int ai = 0; ai < 2; ++ai)
; #pragma unroll
;             for (int m = 0; m < 4; ++m) { const int row = row0 + ai * HALF + m * 16; bf16_t* rowp = O + (size_t)row * ldc + col0;
;                 const float rs = rstd_fix(rv[ai][m]);
; #pragma unroll
;                 for (int bj = 0; bj < 2; ++bj) { const f32x4 v0 = acc[ai][bj][m][0] * rs, v1 = acc[ai][bj][m][1] * rs;
;                     u32x4 w; w.x = pk2(v0[0], v0[1]); w.y = pk2(v0[2], v0[3]); w.z = pk2(v1[0], v1[1]); w.w = pk2(v1[2], v1[3]);
;                     *(u32x4*)(rowp + bj * HALF) = w; } }
	v_lshl_add_u64 v[98:99], s[34:35], 0, v[98:99]
	v_lshl_add_u64 v[98:99], v[98:99], 0, v[154:155]
	s_nop 0
	v_pk_mul_f32 v[96:97], v[96:97], v[100:101] op_sel_hi:[1,0]
	v_pk_mul_f32 v[94:95], v[94:95], v[100:101] op_sel_hi:[1,0]
	v_pk_mul_f32 v[102:103], v[92:93], v[100:101] op_sel_hi:[1,0]
	v_pk_mul_f32 v[92:93], v[90:91], v[100:101] op_sel_hi:[1,0]
	v_cvt_pk_bf16_f32 v90, v94, v95
	v_cvt_pk_bf16_f32 v91, v96, v97
	v_pk_mul_f32 v[88:89], v[88:89], v[100:101] op_sel_hi:[1,0]
	v_cvt_pk_bf16_f32 v92, v92, v93
	v_cvt_pk_bf16_f32 v93, v102, v103
	global_store_dwordx4 v[98:99], v[90:93], off nt
	v_pk_mul_f32 v[86:87], v[86:87], v[100:101] op_sel_hi:[1,0]
	s_nop 0
	v_pk_mul_f32 v[90:91], v[84:85], v[100:101] op_sel_hi:[1,0]
	v_pk_mul_f32 v[84:85], v[82:83], v[100:101] op_sel_hi:[1,0]
	v_cvt_pk_bf16_f32 v82, v86, v87
	v_cvt_pk_bf16_f32 v83, v88, v89
	s_nop 0
	v_cvt_pk_bf16_f32 v84, v84, v85
	v_cvt_pk_bf16_f32 v85, v90, v91
	global_store_dwordx4 v[98:99], v[82:85], off offset:256 nt
	s_nop 1
	v_mov_b32_e32 v84, v242
	v_lshlrev_b64 v[82:83], 13, v[152:153]
	v_lshl_add_u64 v[82:83], s[34:35], 0, v[82:83]
	v_lshl_add_u64 v[82:83], v[82:83], 0, v[154:155]
	s_nop 0
	v_pk_mul_f32 v[80:81], v[80:81], v[84:85] op_sel_hi:[1,0]
	v_pk_mul_f32 v[78:79], v[78:79], v[84:85] op_sel_hi:[1,0]
	v_pk_mul_f32 v[86:87], v[76:77], v[84:85] op_sel_hi:[1,0]
	v_pk_mul_f32 v[76:77], v[74:75], v[84:85] op_sel_hi:[1,0]
	v_cvt_pk_bf16_f32 v74, v78, v79
	v_cvt_pk_bf16_f32 v75, v80, v81
	v_pk_mul_f32 v[72:73], v[72:73], v[84:85] op_sel_hi:[1,0]
	v_cvt_pk_bf16_f32 v76, v76, v77
	v_cvt_pk_bf16_f32 v77, v86, v87
	global_store_dwordx4 v[82:83], v[74:77], off nt
	v_pk_mul_f32 v[70:71], v[70:71], v[84:85] op_sel_hi:[1,0]
	s_nop 0
	v_pk_mul_f32 v[74:75], v[68:69], v[84:85] op_sel_hi:[1,0]
	v_pk_mul_f32 v[68:69], v[66:67], v[84:85] op_sel_hi:[1,0]
	v_cvt_pk_bf16_f32 v66, v70, v71
	v_cvt_pk_bf16_f32 v67, v72, v73
	s_nop 0
	v_cvt_pk_bf16_f32 v68, v68, v69
	v_cvt_pk_bf16_f32 v69, v74, v75
	global_store_dwordx4 v[82:83], v[66:69], off offset:256 nt
	s_nop 1
	v_mov_b32_e32 v68, v243
	v_lshl_add_u64 v[66:67], v[142:143], 0, s[46:47]
	s_mov_b64 s[46:47], 0x120000
	s_nop 0
	s_nop 0
	v_pk_mul_f32 v[62:63], v[62:63], v[68:69] op_sel_hi:[1,0]
	v_pk_mul_f32 v[70:71], v[60:61], v[68:69] op_sel_hi:[1,0]
	v_pk_mul_f32 v[60:61], v[58:59], v[68:69] op_sel_hi:[1,0]
	v_cvt_pk_bf16_f32 v58, v62, v63
	v_add_co_u32_e32 v62, vcc, s1, v142
	v_pk_mul_f32 v[64:65], v[64:65], v[68:69] op_sel_hi:[1,0]
	s_nop 0
	v_addc_co_u32_e32 v63, vcc, 0, v143, vcc
	v_cvt_pk_bf16_f32 v59, v64, v65
	v_cvt_pk_bf16_f32 v60, v60, v61
	v_cvt_pk_bf16_f32 v61, v70, v71
	global_store_dwordx4 v[62:63], v[58:61], off nt
	v_pk_mul_f32 v[56:57], v[56:57], v[68:69] op_sel_hi:[1,0]
	v_pk_mul_f32 v[54:55], v[54:55], v[68:69] op_sel_hi:[1,0]
	v_pk_mul_f32 v[58:59], v[52:53], v[68:69] op_sel_hi:[1,0]
	v_pk_mul_f32 v[52:53], v[50:51], v[68:69] op_sel_hi:[1,0]
	v_cvt_pk_bf16_f32 v50, v54, v55
	v_cvt_pk_bf16_f32 v51, v56, v57
	s_mov_b32 s1, 0x120000
	v_cvt_pk_bf16_f32 v52, v52, v53
	v_cvt_pk_bf16_f32 v53, v58, v59
	global_store_dwordx4 v[66:67], v[50:53], off offset:256 nt
	s_nop 1
	v_mov_b32_e32 v52, v246
	v_lshl_add_u64 v[50:51], v[142:143], 0, s[46:47]
	s_mov_b64 s[46:47], 0x140000
	s_nop 0
	s_nop 0
	v_pk_mul_f32 v[46:47], v[46:47], v[52:53] op_sel_hi:[1,0]
	v_pk_mul_f32 v[54:55], v[44:45], v[52:53] op_sel_hi:[1,0]
	v_pk_mul_f32 v[44:45], v[42:43], v[52:53] op_sel_hi:[1,0]
	v_cvt_pk_bf16_f32 v42, v46, v47
	v_add_co_u32_e32 v46, vcc, s1, v142
	v_pk_mul_f32 v[48:49], v[48:49], v[52:53] op_sel_hi:[1,0]
	s_nop 0
	v_addc_co_u32_e32 v47, vcc, 0, v143, vcc
	v_cvt_pk_bf16_f32 v43, v48, v49
	v_cvt_pk_bf16_f32 v44, v44, v45
	v_cvt_pk_bf16_f32 v45, v54, v55
	global_store_dwordx4 v[46:47], v[42:45], off nt
	v_pk_mul_f32 v[40:41], v[40:41], v[52:53] op_sel_hi:[1,0]
	v_pk_mul_f32 v[38:39], v[38:39], v[52:53] op_sel_hi:[1,0]
	v_pk_mul_f32 v[42:43], v[36:37], v[52:53] op_sel_hi:[1,0]
	v_pk_mul_f32 v[36:37], v[34:35], v[52:53] op_sel_hi:[1,0]
	v_cvt_pk_bf16_f32 v34, v38, v39
	v_cvt_pk_bf16_f32 v35, v40, v41
	s_mov_b32 s1, 0x140000
	v_cvt_pk_bf16_f32 v36, v36, v37
	v_cvt_pk_bf16_f32 v37, v42, v43
	global_store_dwordx4 v[50:51], v[34:37], off offset:256 nt
	s_nop 1
	v_mov_b32_e32 v36, v247
	v_lshl_add_u64 v[34:35], v[142:143], 0, s[46:47]
	s_mov_b64 s[46:47], 0x160000
	s_nop 0
	s_nop 0
	v_pk_mul_f32 v[30:31], v[30:31], v[36:37] op_sel_hi:[1,0]
	v_pk_mul_f32 v[38:39], v[28:29], v[36:37] op_sel_hi:[1,0]
	v_pk_mul_f32 v[28:29], v[26:27], v[36:37] op_sel_hi:[1,0]
	v_cvt_pk_bf16_f32 v26, v30, v31
	v_add_co_u32_e32 v30, vcc, s1, v142
	v_pk_mul_f32 v[32:33], v[32:33], v[36:37] op_sel_hi:[1,0]
	s_nop 0
	v_addc_co_u32_e32 v31, vcc, 0, v143, vcc
	v_cvt_pk_bf16_f32 v27, v32, v33
	v_cvt_pk_bf16_f32 v28, v28, v29
	v_cvt_pk_bf16_f32 v29, v38, v39
	global_store_dwordx4 v[30:31], v[26:29], off nt
	v_pk_mul_f32 v[24:25], v[24:25], v[36:37] op_sel_hi:[1,0]
	v_pk_mul_f32 v[22:23], v[22:23], v[36:37] op_sel_hi:[1,0]
	v_pk_mul_f32 v[26:27], v[20:21], v[36:37] op_sel_hi:[1,0]
	v_pk_mul_f32 v[20:21], v[18:19], v[36:37] op_sel_hi:[1,0]
	v_cvt_pk_bf16_f32 v18, v22, v23
	v_cvt_pk_bf16_f32 v19, v24, v25
	s_mov_b32 s1, 0x160000
	v_cvt_pk_bf16_f32 v20, v20, v21
	v_cvt_pk_bf16_f32 v21, v26, v27
	global_store_dwordx4 v[34:35], v[18:21], off offset:256 nt
	s_nop 1
	v_mov_b32_e32 v20, v248
	v_lshl_add_u64 v[18:19], v[142:143], 0, s[46:47]
	s_mov_b64 s[46:47], s[42:43]
	s_nop 0
	s_nop 0
	v_pk_mul_f32 v[14:15], v[14:15], v[20:21] op_sel_hi:[1,0]
	v_pk_mul_f32 v[22:23], v[12:13], v[20:21] op_sel_hi:[1,0]
	v_pk_mul_f32 v[12:13], v[10:11], v[20:21] op_sel_hi:[1,0]
	v_cvt_pk_bf16_f32 v10, v14, v15
	v_add_co_u32_e32 v14, vcc, s1, v142
	v_pk_mul_f32 v[16:17], v[16:17], v[20:21] op_sel_hi:[1,0]
	s_nop 0
	v_addc_co_u32_e32 v15, vcc, 0, v143, vcc
	v_cvt_pk_bf16_f32 v11, v16, v17
	v_cvt_pk_bf16_f32 v12, v12, v13
	v_cvt_pk_bf16_f32 v13, v22, v23
	global_store_dwordx4 v[14:15], v[10:13], off nt
	s_and_b64 vcc, exec, s[40:41]
	v_pk_mul_f32 v[8:9], v[8:9], v[20:21] op_sel_hi:[1,0]
	v_pk_mul_f32 v[10:11], v[4:5], v[20:21] op_sel_hi:[1,0]
	v_pk_mul_f32 v[4:5], v[2:3], v[20:21] op_sel_hi:[1,0]
	v_pk_mul_f32 v[6:7], v[6:7], v[20:21] op_sel_hi:[1,0]
	s_nop 0
	v_cvt_pk_bf16_f32 v2, v6, v7
	v_cvt_pk_bf16_f32 v3, v8, v9
	v_cvt_pk_bf16_f32 v4, v4, v5
	v_cvt_pk_bf16_f32 v5, v10, v11
	global_store_dwordx4 v[18:19], v[2:5], off offset:256 nt
	s_cbranch_vccz .LBB0_498
	s_waitcnt vmcnt(0)
	v_readlane_b32 s84, v254, 44
	s_cmpk_gt_u32 s2, 0xff
	v_readlane_b32 s85, v254, 45
	s_cbranch_scc1 .LBB0_509
	s_barrier
